# experiment on v2: per-segment s_setprio 1/0 flips removed from all six GEMM K-loops
# speedup vs baseline: 1.0048x; 1.0019x over previous
.LBB0_32:
	s_add_u32 s28, s26, 0xfff00080
	s_addc_u32 s29, s27, -1
	s_add_i32 s33, 0, 0x10000
	s_cmp_eq_u32 s25, 60
	s_cselect_b32 s31, s1, s29
	s_cselect_b32 s30, s2, s28
	s_cselect_b32 s29, s4, s19
	s_cselect_b32 s28, s5, s17
	s_add_i32 s47, 0, 0x14000
	v_add_u32_e32 v80, s33, v214
	v_add_u32_e32 v168, s47, v214
	ds_read_b128 v[68:71], v80
	ds_read_b128 v[72:75], v80 offset:1024
	ds_read_b128 v[76:79], v80 offset:2048
	ds_read_b128 v[80:83], v80 offset:3072
	ds_read_b128 v[148:151], v168
	ds_read_b128 v[160:163], v168 offset:1024
	ds_read_b128 v[164:167], v168 offset:2048
	ds_read_b128 v[168:171], v168 offset:3072
	v_lshl_add_u64 v[212:213], s[26:27], 0, v[154:155]
	s_add_i32 m0, s50, 0xc000
	ds_read_b128 v[172:175], v215
	ds_read_b128 v[176:179], v215 offset:1024
	ds_read_b128 v[188:191], v215 offset:2048
	ds_read_b128 v[192:195], v215 offset:3072
	ds_read_b128 v[196:199], v215 offset:4096
	ds_read_b128 v[200:203], v215 offset:5120
	ds_read_b128 v[204:207], v215 offset:6144
	ds_read_b128 v[208:211], v215 offset:7168
	global_load_lds_dwordx4 v[212:213], off
	v_lshl_add_u64 v[212:213], s[26:27], 0, v[156:157]
	s_add_i32 m0, s50, 0xe000
	s_nop 0
	global_load_lds_dwordx4 v[212:213], off
	s_waitcnt vmcnt(8)
	s_waitcnt lgkmcnt(0)
	s_barrier
	s_waitcnt lgkmcnt(0)
	v_mfma_f32_16x16x32_bf16 v[144:147], v[68:71], v[172:175], v[144:147]
	v_mfma_f32_16x16x32_bf16 v[140:143], v[76:79], v[172:175], v[140:143]
	v_mfma_f32_16x16x32_bf16 v[136:139], v[68:71], v[188:191], v[136:139]
	v_mfma_f32_16x16x32_bf16 v[132:135], v[76:79], v[188:191], v[132:135]
	v_mfma_f32_16x16x32_bf16 v[112:115], v[68:71], v[196:199], v[112:115]
	v_mfma_f32_16x16x32_bf16 v[108:111], v[76:79], v[196:199], v[108:111]
	v_mfma_f32_16x16x32_bf16 v[104:107], v[68:71], v[204:207], v[104:107]
	v_mfma_f32_16x16x32_bf16 v[100:103], v[76:79], v[204:207], v[100:103]
	v_mfma_f32_16x16x32_bf16 v[144:147], v[72:75], v[176:179], v[144:147]
	v_mfma_f32_16x16x32_bf16 v[140:143], v[80:83], v[176:179], v[140:143]
	v_mfma_f32_16x16x32_bf16 v[136:139], v[72:75], v[192:195], v[136:139]
	v_mfma_f32_16x16x32_bf16 v[132:135], v[80:83], v[192:195], v[132:135]
	v_mfma_f32_16x16x32_bf16 v[112:115], v[72:75], v[200:203], v[112:115]
	v_mfma_f32_16x16x32_bf16 v[108:111], v[80:83], v[200:203], v[108:111]
	v_mfma_f32_16x16x32_bf16 v[104:107], v[72:75], v[208:211], v[104:107]
	v_mfma_f32_16x16x32_bf16 v[100:103], v[80:83], v[208:211], v[100:103]
	v_mfma_f32_16x16x32_bf16 v[128:131], v[148:151], v[172:175], v[128:131]
	v_mfma_f32_16x16x32_bf16 v[124:127], v[164:167], v[172:175], v[124:127]
	v_mfma_f32_16x16x32_bf16 v[120:123], v[148:151], v[188:191], v[120:123]
	v_mfma_f32_16x16x32_bf16 v[116:119], v[164:167], v[188:191], v[116:119]
	v_mfma_f32_16x16x32_bf16 v[96:99], v[148:151], v[196:199], v[96:99]
	v_mfma_f32_16x16x32_bf16 v[92:95], v[164:167], v[196:199], v[92:95]
	v_mfma_f32_16x16x32_bf16 v[88:91], v[148:151], v[204:207], v[88:91]
	v_mfma_f32_16x16x32_bf16 v[84:87], v[164:167], v[204:207], v[84:87]
	v_mfma_f32_16x16x32_bf16 v[128:131], v[160:163], v[176:179], v[128:131]
	v_mfma_f32_16x16x32_bf16 v[124:127], v[168:171], v[176:179], v[124:127]
	v_mfma_f32_16x16x32_bf16 v[120:123], v[160:163], v[192:195], v[120:123]
	v_mfma_f32_16x16x32_bf16 v[116:119], v[168:171], v[192:195], v[116:119]
	v_mfma_f32_16x16x32_bf16 v[96:99], v[160:163], v[200:203], v[96:99]
	v_mfma_f32_16x16x32_bf16 v[92:95], v[168:171], v[200:203], v[92:95]
	v_mfma_f32_16x16x32_bf16 v[88:91], v[160:163], v[208:211], v[88:91]
	v_mfma_f32_16x16x32_bf16 v[84:87], v[168:171], v[208:211], v[84:87]
	s_barrier
	s_add_i32 s33, s33, s41
	v_lshl_add_u64 v[212:213], s[28:29], 0, v[180:181]
	s_mov_b32 m0, s33
	ds_read_b128 v[172:175], v215 offset:16384
	ds_read_b128 v[176:179], v215 offset:17408
	ds_read_b128 v[188:191], v215 offset:18432
	ds_read_b128 v[192:195], v215 offset:19456
	ds_read_b128 v[196:199], v215 offset:20480
	ds_read_b128 v[200:203], v215 offset:21504
	ds_read_b128 v[204:207], v215 offset:22528
	ds_read_b128 v[208:211], v215 offset:23552
	global_load_lds_dwordx4 v[212:213], off
	s_add_i32 m0, s33, 0x2000
	s_add_u32 s44, s28, 0x100000
	v_lshl_add_u64 v[216:217], s[28:29], 0, v[152:153]
	s_addc_u32 s45, s29, 0
	s_add_i32 s33, s47, s41
	global_load_lds_dwordx4 v[216:217], off
	v_lshl_add_u64 v[218:219], s[44:45], 0, v[180:181]
	s_mov_b32 m0, s33
	v_lshl_add_u64 v[220:221], s[30:31], 0, v[152:153]
	global_load_lds_dwordx4 v[218:219], off
	v_lshl_add_u64 v[218:219], s[44:45], 0, v[152:153]
	s_add_i32 m0, s33, 0x2000
	s_nop 0
	global_load_lds_dwordx4 v[218:219], off
	v_lshl_add_u64 v[218:219], s[30:31], 0, v[180:181]
	s_mov_b32 m0, s50
	s_nop 0
	global_load_lds_dwordx4 v[218:219], off
	s_mov_b32 m0, s51
	s_nop 0
	global_load_lds_dwordx4 v[220:221], off
	s_waitcnt vmcnt(8)
	s_waitcnt lgkmcnt(0)
	s_barrier
	s_waitcnt lgkmcnt(0)
	v_mfma_f32_16x16x32_bf16 v[64:67], v[68:71], v[172:175], v[64:67]
	v_mfma_f32_16x16x32_bf16 v[60:63], v[76:79], v[172:175], v[60:63]
	v_mfma_f32_16x16x32_bf16 v[56:59], v[68:71], v[188:191], v[56:59]
	v_mfma_f32_16x16x32_bf16 v[52:55], v[76:79], v[188:191], v[52:55]
	v_mfma_f32_16x16x32_bf16 v[32:35], v[68:71], v[196:199], v[32:35]
	v_mfma_f32_16x16x32_bf16 v[28:31], v[76:79], v[196:199], v[28:31]
	v_mfma_f32_16x16x32_bf16 v[16:19], v[68:71], v[204:207], v[16:19]
	v_mfma_f32_16x16x32_bf16 v[12:15], v[76:79], v[204:207], v[12:15]
	v_mfma_f32_16x16x32_bf16 v[64:67], v[72:75], v[176:179], v[64:67]
	v_mfma_f32_16x16x32_bf16 v[60:63], v[80:83], v[176:179], v[60:63]
	v_mfma_f32_16x16x32_bf16 v[56:59], v[72:75], v[192:195], v[56:59]
	v_mfma_f32_16x16x32_bf16 v[52:55], v[80:83], v[192:195], v[52:55]
	v_mfma_f32_16x16x32_bf16 v[32:35], v[72:75], v[200:203], v[32:35]
	v_mfma_f32_16x16x32_bf16 v[28:31], v[80:83], v[200:203], v[28:31]
	v_mfma_f32_16x16x32_bf16 v[16:19], v[72:75], v[208:211], v[16:19]
	v_mfma_f32_16x16x32_bf16 v[12:15], v[80:83], v[208:211], v[12:15]
	v_mfma_f32_16x16x32_bf16 v[48:51], v[148:151], v[172:175], v[48:51]
	v_mfma_f32_16x16x32_bf16 v[44:47], v[164:167], v[172:175], v[44:47]
	v_mfma_f32_16x16x32_bf16 v[40:43], v[148:151], v[188:191], v[40:43]
	v_mfma_f32_16x16x32_bf16 v[36:39], v[164:167], v[188:191], v[36:39]
	v_mfma_f32_16x16x32_bf16 v[24:27], v[148:151], v[196:199], v[24:27]
	v_mfma_f32_16x16x32_bf16 v[20:23], v[164:167], v[196:199], v[20:23]
	v_mfma_f32_16x16x32_bf16 v[8:11], v[148:151], v[204:207], v[8:11]
	v_mfma_f32_16x16x32_bf16 v[4:7], v[164:167], v[204:207], v[4:7]
	v_mfma_f32_16x16x32_bf16 v[48:51], v[160:163], v[176:179], v[48:51]
	v_mfma_f32_16x16x32_bf16 v[44:47], v[168:171], v[176:179], v[44:47]
	v_mfma_f32_16x16x32_bf16 v[40:43], v[160:163], v[192:195], v[40:43]
	v_mfma_f32_16x16x32_bf16 v[36:39], v[168:171], v[192:195], v[36:39]
	v_mfma_f32_16x16x32_bf16 v[24:27], v[160:163], v[200:203], v[24:27]
	v_mfma_f32_16x16x32_bf16 v[20:23], v[168:171], v[200:203], v[20:23]
	v_mfma_f32_16x16x32_bf16 v[8:11], v[160:163], v[208:211], v[8:11]
	v_mfma_f32_16x16x32_bf16 v[4:7], v[168:171], v[208:211], v[4:7]
	s_barrier
	s_add_i32 s33, 0, 0x18000
	s_add_i32 s44, 0, 0x1c000
	v_add_u32_e32 v80, s33, v214
	v_add_u32_e32 v168, s44, v214
	ds_read_b128 v[68:71], v80
	ds_read_b128 v[72:75], v80 offset:1024
	ds_read_b128 v[76:79], v80 offset:2048
	ds_read_b128 v[80:83], v80 offset:3072
	ds_read_b128 v[148:151], v168
	ds_read_b128 v[160:163], v168 offset:1024
	ds_read_b128 v[164:167], v168 offset:2048
	ds_read_b128 v[168:171], v168 offset:3072
	s_add_u32 s30, s30, 0x100000
	s_addc_u32 s31, s31, 0
	s_mov_b32 m0, s57
	v_lshl_add_u64 v[222:223], s[30:31], 0, v[180:181]
	ds_read_b128 v[172:175], v215 offset:32768
	ds_read_b128 v[176:179], v215 offset:33792
	ds_read_b128 v[188:191], v215 offset:34816
	ds_read_b128 v[192:195], v215 offset:35840
	ds_read_b128 v[196:199], v215 offset:36864
	ds_read_b128 v[200:203], v215 offset:37888
	ds_read_b128 v[204:207], v215 offset:38912
	ds_read_b128 v[208:211], v215 offset:39936
	global_load_lds_dwordx4 v[222:223], off
	v_lshl_add_u64 v[222:223], s[30:31], 0, v[152:153]
	s_mov_b32 m0, s58
	s_nop 0
	global_load_lds_dwordx4 v[222:223], off
	s_waitcnt vmcnt(8)
	s_waitcnt lgkmcnt(0)
	s_barrier
	s_waitcnt lgkmcnt(0)
	v_mfma_f32_16x16x32_bf16 v[144:147], v[68:71], v[172:175], v[144:147]
	v_mfma_f32_16x16x32_bf16 v[140:143], v[76:79], v[172:175], v[140:143]
	v_mfma_f32_16x16x32_bf16 v[136:139], v[68:71], v[188:191], v[136:139]
	v_mfma_f32_16x16x32_bf16 v[132:135], v[76:79], v[188:191], v[132:135]
	v_mfma_f32_16x16x32_bf16 v[112:115], v[68:71], v[196:199], v[112:115]
	v_mfma_f32_16x16x32_bf16 v[108:111], v[76:79], v[196:199], v[108:111]
	v_mfma_f32_16x16x32_bf16 v[104:107], v[68:71], v[204:207], v[104:107]
	v_mfma_f32_16x16x32_bf16 v[100:103], v[76:79], v[204:207], v[100:103]
	v_mfma_f32_16x16x32_bf16 v[144:147], v[72:75], v[176:179], v[144:147]
	v_mfma_f32_16x16x32_bf16 v[140:143], v[80:83], v[176:179], v[140:143]
	v_mfma_f32_16x16x32_bf16 v[136:139], v[72:75], v[192:195], v[136:139]
	v_mfma_f32_16x16x32_bf16 v[132:135], v[80:83], v[192:195], v[132:135]
	v_mfma_f32_16x16x32_bf16 v[112:115], v[72:75], v[200:203], v[112:115]
	v_mfma_f32_16x16x32_bf16 v[108:111], v[80:83], v[200:203], v[108:111]
	v_mfma_f32_16x16x32_bf16 v[104:107], v[72:75], v[208:211], v[104:107]
	v_mfma_f32_16x16x32_bf16 v[100:103], v[80:83], v[208:211], v[100:103]
	v_mfma_f32_16x16x32_bf16 v[128:131], v[148:151], v[172:175], v[128:131]
	v_mfma_f32_16x16x32_bf16 v[124:127], v[164:167], v[172:175], v[124:127]
	v_mfma_f32_16x16x32_bf16 v[120:123], v[148:151], v[188:191], v[120:123]
	v_mfma_f32_16x16x32_bf16 v[116:119], v[164:167], v[188:191], v[116:119]
	v_mfma_f32_16x16x32_bf16 v[96:99], v[148:151], v[196:199], v[96:99]
	v_mfma_f32_16x16x32_bf16 v[92:95], v[164:167], v[196:199], v[92:95]
	v_mfma_f32_16x16x32_bf16 v[88:91], v[148:151], v[204:207], v[88:91]
	v_mfma_f32_16x16x32_bf16 v[84:87], v[164:167], v[204:207], v[84:87]
	v_mfma_f32_16x16x32_bf16 v[128:131], v[160:163], v[176:179], v[128:131]
	v_mfma_f32_16x16x32_bf16 v[124:127], v[168:171], v[176:179], v[124:127]
	v_mfma_f32_16x16x32_bf16 v[120:123], v[160:163], v[192:195], v[120:123]
	v_mfma_f32_16x16x32_bf16 v[116:119], v[168:171], v[192:195], v[116:119]
	v_mfma_f32_16x16x32_bf16 v[96:99], v[160:163], v[200:203], v[96:99]
	v_mfma_f32_16x16x32_bf16 v[92:95], v[168:171], v[200:203], v[92:95]
	v_mfma_f32_16x16x32_bf16 v[88:91], v[160:163], v[208:211], v[88:91]
	v_mfma_f32_16x16x32_bf16 v[84:87], v[168:171], v[208:211], v[84:87]
	s_barrier
	s_add_i32 s30, s33, s41
	v_lshl_add_u64 v[212:213], v[212:213], 0, s[52:53]
	s_mov_b32 m0, s30
	ds_read_b128 v[172:175], v215 offset:49152
	ds_read_b128 v[176:179], v215 offset:50176
	ds_read_b128 v[188:191], v215 offset:51200
	ds_read_b128 v[192:195], v215 offset:52224
	ds_read_b128 v[196:199], v215 offset:53248
	ds_read_b128 v[200:203], v215 offset:54272
	ds_read_b128 v[204:207], v215 offset:55296
	ds_read_b128 v[208:211], v215 offset:56320
	global_load_lds_dwordx4 v[212:213], off
	s_add_i32 m0, s30, 0x2000
	s_add_u32 s28, s28, 0x100080
	v_lshl_add_u64 v[212:213], v[216:217], 0, s[52:53]
	s_addc_u32 s29, s29, 0
	s_add_i32 s30, s44, s41
	global_load_lds_dwordx4 v[212:213], off
	v_lshl_add_u64 v[212:213], s[28:29], 0, v[180:181]
	s_mov_b32 m0, s30
	s_nop 0
	global_load_lds_dwordx4 v[212:213], off
	v_lshl_add_u64 v[212:213], s[28:29], 0, v[152:153]
	s_add_i32 m0, s30, 0x2000
	s_nop 0
	global_load_lds_dwordx4 v[212:213], off
	v_lshl_add_u64 v[212:213], v[218:219], 0, s[52:53]
	s_mov_b32 m0, s83
	s_nop 0
	global_load_lds_dwordx4 v[212:213], off
	v_lshl_add_u64 v[212:213], v[220:221], 0, s[52:53]
	s_mov_b32 m0, s84
	s_nop 0
	global_load_lds_dwordx4 v[212:213], off
	s_waitcnt vmcnt(8)
	s_waitcnt lgkmcnt(0)
	s_barrier
	s_waitcnt lgkmcnt(0)
	v_mfma_f32_16x16x32_bf16 v[64:67], v[68:71], v[172:175], v[64:67]
	v_mfma_f32_16x16x32_bf16 v[60:63], v[76:79], v[172:175], v[60:63]
	v_mfma_f32_16x16x32_bf16 v[56:59], v[68:71], v[188:191], v[56:59]
	v_mfma_f32_16x16x32_bf16 v[52:55], v[76:79], v[188:191], v[52:55]
	v_mfma_f32_16x16x32_bf16 v[32:35], v[68:71], v[196:199], v[32:35]
	v_mfma_f32_16x16x32_bf16 v[28:31], v[76:79], v[196:199], v[28:31]
	v_mfma_f32_16x16x32_bf16 v[16:19], v[68:71], v[204:207], v[16:19]
	v_mfma_f32_16x16x32_bf16 v[12:15], v[76:79], v[204:207], v[12:15]
	v_mfma_f32_16x16x32_bf16 v[64:67], v[72:75], v[176:179], v[64:67]
	v_mfma_f32_16x16x32_bf16 v[60:63], v[80:83], v[176:179], v[60:63]
	v_mfma_f32_16x16x32_bf16 v[56:59], v[72:75], v[192:195], v[56:59]
	v_mfma_f32_16x16x32_bf16 v[52:55], v[80:83], v[192:195], v[52:55]
	v_mfma_f32_16x16x32_bf16 v[32:35], v[72:75], v[200:203], v[32:35]
	v_mfma_f32_16x16x32_bf16 v[28:31], v[80:83], v[200:203], v[28:31]
	v_mfma_f32_16x16x32_bf16 v[16:19], v[72:75], v[208:211], v[16:19]
	v_mfma_f32_16x16x32_bf16 v[12:15], v[80:83], v[208:211], v[12:15]
	v_mfma_f32_16x16x32_bf16 v[48:51], v[148:151], v[172:175], v[48:51]
	v_mfma_f32_16x16x32_bf16 v[44:47], v[164:167], v[172:175], v[44:47]
	v_mfma_f32_16x16x32_bf16 v[40:43], v[148:151], v[188:191], v[40:43]
	v_mfma_f32_16x16x32_bf16 v[36:39], v[164:167], v[188:191], v[36:39]
	v_mfma_f32_16x16x32_bf16 v[24:27], v[148:151], v[196:199], v[24:27]
	v_mfma_f32_16x16x32_bf16 v[20:23], v[164:167], v[196:199], v[20:23]
	v_mfma_f32_16x16x32_bf16 v[8:11], v[148:151], v[204:207], v[8:11]
	v_mfma_f32_16x16x32_bf16 v[4:7], v[164:167], v[204:207], v[4:7]
	v_mfma_f32_16x16x32_bf16 v[48:51], v[160:163], v[176:179], v[48:51]
	v_mfma_f32_16x16x32_bf16 v[44:47], v[168:171], v[176:179], v[44:47]
	v_mfma_f32_16x16x32_bf16 v[40:43], v[160:163], v[192:195], v[40:43]
	v_mfma_f32_16x16x32_bf16 v[36:39], v[168:171], v[192:195], v[36:39]
	v_mfma_f32_16x16x32_bf16 v[24:27], v[160:163], v[200:203], v[24:27]
	v_mfma_f32_16x16x32_bf16 v[20:23], v[168:171], v[200:203], v[20:23]
	v_mfma_f32_16x16x32_bf16 v[8:11], v[160:163], v[208:211], v[8:11]
	v_mfma_f32_16x16x32_bf16 v[4:7], v[168:171], v[208:211], v[4:7]
	s_barrier
	s_add_i32 s25, s25, 2
	s_add_u32 s26, s26, 0x100
	s_addc_u32 s27, s27, 0
	s_add_u32 s17, s17, 0x100
	s_addc_u32 s19, s19, 0
	s_cmp_gt_u32 s25, 61
	s_cbranch_scc0 .LBB0_32
	s_and_b64 vcc, exec, s[12:13]
	s_cbranch_vccz .LBB0_35
	s_barrier

.LBB0_76:
	s_add_i32 s29, s27, 2
	s_add_u32 s33, s30, 0xfff00080
	s_addc_u32 s34, s31, -1
	s_add_i32 s44, 0, 0x10000
	s_cmp_eq_u32 s15, s27
	s_cselect_b32 s37, s2, s34
	s_cselect_b32 s36, s4, s33
	s_cselect_b32 s35, s5, s19
	s_cselect_b32 s34, s7, s17
	s_add_i32 s27, 0, 0x14000
	v_add_u32_e32 v112, s44, v212
	v_add_u32_e32 v166, s27, v212
	ds_read_b128 v[76:79], v112
	ds_read_b128 v[84:87], v112 offset:1024
	ds_read_b128 v[96:99], v112 offset:2048
	ds_read_b128 v[112:115], v112 offset:3072
	ds_read_b128 v[148:151], v166
	ds_read_b128 v[158:161], v166 offset:1024
	ds_read_b128 v[162:165], v166 offset:2048
	ds_read_b128 v[166:169], v166 offset:3072
	v_lshl_add_u64 v[178:179], s[30:31], 0, v[154:155]
	s_add_i32 m0, s43, 0xc000
	ds_read_b128 v[170:173], v213
	ds_read_b128 v[174:177], v213 offset:1024
	ds_read_b128 v[188:191], v213 offset:2048
	ds_read_b128 v[192:195], v213 offset:3072
	ds_read_b128 v[196:199], v213 offset:4096
	ds_read_b128 v[200:203], v213 offset:5120
	ds_read_b128 v[204:207], v213 offset:6144
	ds_read_b128 v[208:211], v213 offset:7168
	global_load_lds_dwordx4 v[178:179], off
	v_lshl_add_u64 v[178:179], s[30:31], 0, v[156:157]
	s_add_i32 m0, s43, 0xe000
	s_nop 0
	global_load_lds_dwordx4 v[178:179], off
	s_waitcnt vmcnt(8)
	s_waitcnt lgkmcnt(0)
	s_barrier
	s_waitcnt lgkmcnt(0)
	v_mfma_f32_16x16x32_bf16 v[144:147], v[76:79], v[170:173], v[144:147]
	v_mfma_f32_16x16x32_bf16 v[140:143], v[96:99], v[170:173], v[140:143]
	v_mfma_f32_16x16x32_bf16 v[136:139], v[76:79], v[188:191], v[136:139]
	v_mfma_f32_16x16x32_bf16 v[132:135], v[96:99], v[188:191], v[132:135]
	v_mfma_f32_16x16x32_bf16 v[108:111], v[76:79], v[196:199], v[108:111]
	v_mfma_f32_16x16x32_bf16 v[104:107], v[96:99], v[196:199], v[104:107]
	v_mfma_f32_16x16x32_bf16 v[100:103], v[76:79], v[204:207], v[100:103]
	v_mfma_f32_16x16x32_bf16 v[92:95], v[96:99], v[204:207], v[92:95]
	v_mfma_f32_16x16x32_bf16 v[144:147], v[84:87], v[174:177], v[144:147]
	v_mfma_f32_16x16x32_bf16 v[140:143], v[112:115], v[174:177], v[140:143]
	v_mfma_f32_16x16x32_bf16 v[136:139], v[84:87], v[192:195], v[136:139]
	v_mfma_f32_16x16x32_bf16 v[132:135], v[112:115], v[192:195], v[132:135]
	v_mfma_f32_16x16x32_bf16 v[108:111], v[84:87], v[200:203], v[108:111]
	v_mfma_f32_16x16x32_bf16 v[104:107], v[112:115], v[200:203], v[104:107]
	v_mfma_f32_16x16x32_bf16 v[100:103], v[84:87], v[208:211], v[100:103]
	v_mfma_f32_16x16x32_bf16 v[92:95], v[112:115], v[208:211], v[92:95]
	v_mfma_f32_16x16x32_bf16 v[128:131], v[148:151], v[170:173], v[128:131]
	v_mfma_f32_16x16x32_bf16 v[124:127], v[162:165], v[170:173], v[124:127]
	v_mfma_f32_16x16x32_bf16 v[120:123], v[148:151], v[188:191], v[120:123]
	v_mfma_f32_16x16x32_bf16 v[116:119], v[162:165], v[188:191], v[116:119]
	v_mfma_f32_16x16x32_bf16 v[88:91], v[148:151], v[196:199], v[88:91]
	v_mfma_f32_16x16x32_bf16 v[80:83], v[162:165], v[196:199], v[80:83]
	v_mfma_f32_16x16x32_bf16 v[72:75], v[148:151], v[204:207], v[72:75]
	v_mfma_f32_16x16x32_bf16 v[68:71], v[162:165], v[204:207], v[68:71]
	v_mfma_f32_16x16x32_bf16 v[128:131], v[158:161], v[174:177], v[128:131]
	v_mfma_f32_16x16x32_bf16 v[124:127], v[166:169], v[174:177], v[124:127]
	v_mfma_f32_16x16x32_bf16 v[120:123], v[158:161], v[192:195], v[120:123]
	v_mfma_f32_16x16x32_bf16 v[116:119], v[166:169], v[192:195], v[116:119]
	v_mfma_f32_16x16x32_bf16 v[88:91], v[158:161], v[200:203], v[88:91]
	v_mfma_f32_16x16x32_bf16 v[80:83], v[166:169], v[200:203], v[80:83]
	v_mfma_f32_16x16x32_bf16 v[72:75], v[158:161], v[208:211], v[72:75]
	v_mfma_f32_16x16x32_bf16 v[68:71], v[166:169], v[208:211], v[68:71]
	s_barrier
	s_add_i32 s33, s44, s42
	v_lshl_add_u64 v[178:179], s[34:35], 0, v[180:181]
	s_mov_b32 m0, s33
	ds_read_b128 v[170:173], v213 offset:16384
	ds_read_b128 v[174:177], v213 offset:17408
	ds_read_b128 v[188:191], v213 offset:18432
	ds_read_b128 v[192:195], v213 offset:19456
	ds_read_b128 v[196:199], v213 offset:20480
	ds_read_b128 v[200:203], v213 offset:21504
	ds_read_b128 v[204:207], v213 offset:22528
	ds_read_b128 v[208:211], v213 offset:23552
	global_load_lds_dwordx4 v[178:179], off
	s_add_i32 m0, s33, 0x2000
	s_add_u32 s44, s34, 0x100000
	v_lshl_add_u64 v[214:215], s[34:35], 0, v[152:153]
	s_addc_u32 s45, s35, 0
	s_add_i32 s27, s27, s42
	global_load_lds_dwordx4 v[214:215], off
	v_lshl_add_u64 v[216:217], s[44:45], 0, v[180:181]
	s_mov_b32 m0, s27
	v_lshl_add_u64 v[218:219], s[36:37], 0, v[152:153]
	global_load_lds_dwordx4 v[216:217], off
	v_lshl_add_u64 v[216:217], s[44:45], 0, v[152:153]
	s_add_i32 m0, s27, 0x2000
	s_nop 0
	global_load_lds_dwordx4 v[216:217], off
	v_lshl_add_u64 v[216:217], s[36:37], 0, v[180:181]
	s_mov_b32 m0, s43
	s_nop 0
	global_load_lds_dwordx4 v[216:217], off
	s_mov_b32 m0, s50
	s_nop 0
	global_load_lds_dwordx4 v[218:219], off
	s_waitcnt vmcnt(8)
	s_waitcnt lgkmcnt(0)
	s_barrier
	s_waitcnt lgkmcnt(0)
	v_mfma_f32_16x16x32_bf16 v[64:67], v[76:79], v[170:173], v[64:67]
	v_mfma_f32_16x16x32_bf16 v[60:63], v[96:99], v[170:173], v[60:63]
	v_mfma_f32_16x16x32_bf16 v[56:59], v[76:79], v[188:191], v[56:59]
	v_mfma_f32_16x16x32_bf16 v[52:55], v[96:99], v[188:191], v[52:55]
	v_mfma_f32_16x16x32_bf16 v[32:35], v[76:79], v[196:199], v[32:35]
	v_mfma_f32_16x16x32_bf16 v[28:31], v[96:99], v[196:199], v[28:31]
	v_mfma_f32_16x16x32_bf16 v[16:19], v[76:79], v[204:207], v[16:19]
	v_mfma_f32_16x16x32_bf16 v[12:15], v[96:99], v[204:207], v[12:15]
	v_mfma_f32_16x16x32_bf16 v[64:67], v[84:87], v[174:177], v[64:67]
	v_mfma_f32_16x16x32_bf16 v[60:63], v[112:115], v[174:177], v[60:63]
	v_mfma_f32_16x16x32_bf16 v[56:59], v[84:87], v[192:195], v[56:59]
	v_mfma_f32_16x16x32_bf16 v[52:55], v[112:115], v[192:195], v[52:55]
	v_mfma_f32_16x16x32_bf16 v[32:35], v[84:87], v[200:203], v[32:35]
	v_mfma_f32_16x16x32_bf16 v[28:31], v[112:115], v[200:203], v[28:31]
	v_mfma_f32_16x16x32_bf16 v[16:19], v[84:87], v[208:211], v[16:19]
	v_mfma_f32_16x16x32_bf16 v[12:15], v[112:115], v[208:211], v[12:15]
	v_mfma_f32_16x16x32_bf16 v[48:51], v[148:151], v[170:173], v[48:51]
	v_mfma_f32_16x16x32_bf16 v[44:47], v[162:165], v[170:173], v[44:47]
	v_mfma_f32_16x16x32_bf16 v[40:43], v[148:151], v[188:191], v[40:43]
	v_mfma_f32_16x16x32_bf16 v[36:39], v[162:165], v[188:191], v[36:39]
	v_mfma_f32_16x16x32_bf16 v[24:27], v[148:151], v[196:199], v[24:27]
	v_mfma_f32_16x16x32_bf16 v[20:23], v[162:165], v[196:199], v[20:23]
	v_mfma_f32_16x16x32_bf16 v[8:11], v[148:151], v[204:207], v[8:11]
	v_mfma_f32_16x16x32_bf16 v[4:7], v[162:165], v[204:207], v[4:7]
	v_mfma_f32_16x16x32_bf16 v[48:51], v[158:161], v[174:177], v[48:51]
	v_mfma_f32_16x16x32_bf16 v[44:47], v[166:169], v[174:177], v[44:47]
	v_mfma_f32_16x16x32_bf16 v[40:43], v[158:161], v[192:195], v[40:43]
	v_mfma_f32_16x16x32_bf16 v[36:39], v[166:169], v[192:195], v[36:39]
	v_mfma_f32_16x16x32_bf16 v[24:27], v[158:161], v[200:203], v[24:27]
	v_mfma_f32_16x16x32_bf16 v[20:23], v[166:169], v[200:203], v[20:23]
	v_mfma_f32_16x16x32_bf16 v[8:11], v[158:161], v[208:211], v[8:11]
	v_mfma_f32_16x16x32_bf16 v[4:7], v[166:169], v[208:211], v[4:7]
	s_barrier
	s_add_i32 s27, 0, 0x18000
	s_add_i32 s33, 0, 0x1c000
	v_add_u32_e32 v112, s27, v212
	v_add_u32_e32 v166, s33, v212
	ds_read_b128 v[76:79], v112
	ds_read_b128 v[84:87], v112 offset:1024
	ds_read_b128 v[96:99], v112 offset:2048
	ds_read_b128 v[112:115], v112 offset:3072
	ds_read_b128 v[148:151], v166
	ds_read_b128 v[158:161], v166 offset:1024
	ds_read_b128 v[162:165], v166 offset:2048
	ds_read_b128 v[166:169], v166 offset:3072
	s_add_u32 s36, s36, 0x100000
	s_addc_u32 s37, s37, 0
	s_mov_b32 m0, s51
	v_lshl_add_u64 v[220:221], s[36:37], 0, v[180:181]
	ds_read_b128 v[170:173], v213 offset:32768
	ds_read_b128 v[174:177], v213 offset:33792
	ds_read_b128 v[188:191], v213 offset:34816
	ds_read_b128 v[192:195], v213 offset:35840
	ds_read_b128 v[196:199], v213 offset:36864
	ds_read_b128 v[200:203], v213 offset:37888
	ds_read_b128 v[204:207], v213 offset:38912
	ds_read_b128 v[208:211], v213 offset:39936
	global_load_lds_dwordx4 v[220:221], off
	v_lshl_add_u64 v[220:221], s[36:37], 0, v[152:153]
	s_mov_b32 m0, s57
	s_nop 0
	global_load_lds_dwordx4 v[220:221], off
	s_waitcnt vmcnt(8)
	s_waitcnt lgkmcnt(0)
	s_barrier
	s_waitcnt lgkmcnt(0)
	v_mfma_f32_16x16x32_bf16 v[144:147], v[76:79], v[170:173], v[144:147]
	v_mfma_f32_16x16x32_bf16 v[140:143], v[96:99], v[170:173], v[140:143]
	v_mfma_f32_16x16x32_bf16 v[136:139], v[76:79], v[188:191], v[136:139]
	v_mfma_f32_16x16x32_bf16 v[132:135], v[96:99], v[188:191], v[132:135]
	v_mfma_f32_16x16x32_bf16 v[108:111], v[76:79], v[196:199], v[108:111]
	v_mfma_f32_16x16x32_bf16 v[104:107], v[96:99], v[196:199], v[104:107]
	v_mfma_f32_16x16x32_bf16 v[100:103], v[76:79], v[204:207], v[100:103]
	v_mfma_f32_16x16x32_bf16 v[92:95], v[96:99], v[204:207], v[92:95]
	v_mfma_f32_16x16x32_bf16 v[144:147], v[84:87], v[174:177], v[144:147]
	v_mfma_f32_16x16x32_bf16 v[140:143], v[112:115], v[174:177], v[140:143]
	v_mfma_f32_16x16x32_bf16 v[136:139], v[84:87], v[192:195], v[136:139]
	v_mfma_f32_16x16x32_bf16 v[132:135], v[112:115], v[192:195], v[132:135]
	v_mfma_f32_16x16x32_bf16 v[108:111], v[84:87], v[200:203], v[108:111]
	v_mfma_f32_16x16x32_bf16 v[104:107], v[112:115], v[200:203], v[104:107]
	v_mfma_f32_16x16x32_bf16 v[100:103], v[84:87], v[208:211], v[100:103]
	v_mfma_f32_16x16x32_bf16 v[92:95], v[112:115], v[208:211], v[92:95]
	v_mfma_f32_16x16x32_bf16 v[128:131], v[148:151], v[170:173], v[128:131]
	v_mfma_f32_16x16x32_bf16 v[124:127], v[162:165], v[170:173], v[124:127]
	v_mfma_f32_16x16x32_bf16 v[120:123], v[148:151], v[188:191], v[120:123]
	v_mfma_f32_16x16x32_bf16 v[116:119], v[162:165], v[188:191], v[116:119]
	v_mfma_f32_16x16x32_bf16 v[88:91], v[148:151], v[196:199], v[88:91]
	v_mfma_f32_16x16x32_bf16 v[80:83], v[162:165], v[196:199], v[80:83]
	v_mfma_f32_16x16x32_bf16 v[72:75], v[148:151], v[204:207], v[72:75]
	v_mfma_f32_16x16x32_bf16 v[68:71], v[162:165], v[204:207], v[68:71]
	v_mfma_f32_16x16x32_bf16 v[128:131], v[158:161], v[174:177], v[128:131]
	v_mfma_f32_16x16x32_bf16 v[124:127], v[166:169], v[174:177], v[124:127]
	v_mfma_f32_16x16x32_bf16 v[120:123], v[158:161], v[192:195], v[120:123]
	v_mfma_f32_16x16x32_bf16 v[116:119], v[166:169], v[192:195], v[116:119]
	v_mfma_f32_16x16x32_bf16 v[88:91], v[158:161], v[200:203], v[88:91]
	v_mfma_f32_16x16x32_bf16 v[80:83], v[166:169], v[200:203], v[80:83]
	v_mfma_f32_16x16x32_bf16 v[72:75], v[158:161], v[208:211], v[72:75]
	v_mfma_f32_16x16x32_bf16 v[68:71], v[166:169], v[208:211], v[68:71]
	s_barrier
	s_add_i32 s27, s27, s42
	v_lshl_add_u64 v[178:179], v[178:179], 0, s[52:53]
	s_mov_b32 m0, s27
	ds_read_b128 v[170:173], v213 offset:49152
	ds_read_b128 v[174:177], v213 offset:50176
	ds_read_b128 v[188:191], v213 offset:51200
	ds_read_b128 v[192:195], v213 offset:52224
	ds_read_b128 v[196:199], v213 offset:53248
	ds_read_b128 v[200:203], v213 offset:54272
	ds_read_b128 v[204:207], v213 offset:55296
	ds_read_b128 v[208:211], v213 offset:56320
	global_load_lds_dwordx4 v[178:179], off
	s_add_i32 m0, s27, 0x2000
	s_add_u32 s34, s34, 0x100080
	v_lshl_add_u64 v[178:179], v[214:215], 0, s[52:53]
	s_addc_u32 s35, s35, 0
	s_add_i32 s27, s33, s42
	global_load_lds_dwordx4 v[178:179], off
	v_lshl_add_u64 v[178:179], s[34:35], 0, v[180:181]
	s_mov_b32 m0, s27
	s_nop 0
	global_load_lds_dwordx4 v[178:179], off
	v_lshl_add_u64 v[178:179], s[34:35], 0, v[152:153]
	s_add_i32 m0, s27, 0x2000
	s_nop 0
	global_load_lds_dwordx4 v[178:179], off
	v_lshl_add_u64 v[178:179], v[216:217], 0, s[52:53]
	s_mov_b32 m0, s84
	s_nop 0
	global_load_lds_dwordx4 v[178:179], off
	v_lshl_add_u64 v[178:179], v[218:219], 0, s[52:53]
	s_mov_b32 m0, s85
	s_nop 0
	global_load_lds_dwordx4 v[178:179], off
	s_waitcnt vmcnt(8)
	s_waitcnt lgkmcnt(0)
	s_barrier
	s_waitcnt lgkmcnt(0)
	v_mfma_f32_16x16x32_bf16 v[64:67], v[76:79], v[170:173], v[64:67]
	v_mfma_f32_16x16x32_bf16 v[60:63], v[96:99], v[170:173], v[60:63]
	v_mfma_f32_16x16x32_bf16 v[56:59], v[76:79], v[188:191], v[56:59]
	v_mfma_f32_16x16x32_bf16 v[52:55], v[96:99], v[188:191], v[52:55]
	v_mfma_f32_16x16x32_bf16 v[32:35], v[76:79], v[196:199], v[32:35]
	v_mfma_f32_16x16x32_bf16 v[28:31], v[96:99], v[196:199], v[28:31]
	v_mfma_f32_16x16x32_bf16 v[16:19], v[76:79], v[204:207], v[16:19]
	v_mfma_f32_16x16x32_bf16 v[12:15], v[96:99], v[204:207], v[12:15]
	v_mfma_f32_16x16x32_bf16 v[64:67], v[84:87], v[174:177], v[64:67]
	v_mfma_f32_16x16x32_bf16 v[60:63], v[112:115], v[174:177], v[60:63]
	v_mfma_f32_16x16x32_bf16 v[56:59], v[84:87], v[192:195], v[56:59]
	v_mfma_f32_16x16x32_bf16 v[52:55], v[112:115], v[192:195], v[52:55]
	v_mfma_f32_16x16x32_bf16 v[32:35], v[84:87], v[200:203], v[32:35]
	v_mfma_f32_16x16x32_bf16 v[28:31], v[112:115], v[200:203], v[28:31]
	v_mfma_f32_16x16x32_bf16 v[16:19], v[84:87], v[208:211], v[16:19]
	v_mfma_f32_16x16x32_bf16 v[12:15], v[112:115], v[208:211], v[12:15]
	v_mfma_f32_16x16x32_bf16 v[48:51], v[148:151], v[170:173], v[48:51]
	v_mfma_f32_16x16x32_bf16 v[44:47], v[162:165], v[170:173], v[44:47]
	v_mfma_f32_16x16x32_bf16 v[40:43], v[148:151], v[188:191], v[40:43]
	v_mfma_f32_16x16x32_bf16 v[36:39], v[162:165], v[188:191], v[36:39]
	v_mfma_f32_16x16x32_bf16 v[24:27], v[148:151], v[196:199], v[24:27]
	v_mfma_f32_16x16x32_bf16 v[20:23], v[162:165], v[196:199], v[20:23]
	v_mfma_f32_16x16x32_bf16 v[8:11], v[148:151], v[204:207], v[8:11]
	v_mfma_f32_16x16x32_bf16 v[4:7], v[162:165], v[204:207], v[4:7]
	v_mfma_f32_16x16x32_bf16 v[48:51], v[158:161], v[174:177], v[48:51]
	v_mfma_f32_16x16x32_bf16 v[44:47], v[166:169], v[174:177], v[44:47]
	v_mfma_f32_16x16x32_bf16 v[40:43], v[158:161], v[192:195], v[40:43]
	v_mfma_f32_16x16x32_bf16 v[36:39], v[166:169], v[192:195], v[36:39]
	v_mfma_f32_16x16x32_bf16 v[24:27], v[158:161], v[200:203], v[24:27]
	v_mfma_f32_16x16x32_bf16 v[20:23], v[166:169], v[200:203], v[20:23]
	v_mfma_f32_16x16x32_bf16 v[8:11], v[158:161], v[208:211], v[8:11]
	v_mfma_f32_16x16x32_bf16 v[4:7], v[166:169], v[208:211], v[4:7]
	s_barrier
	s_add_u32 s30, s30, 0x100
	s_addc_u32 s31, s31, 0
	s_add_u32 s17, s17, 0x100
	s_addc_u32 s19, s19, 0
	s_cmp_ge_i32 s29, s1
	s_mov_b32 s27, s29
	s_cbranch_scc0 .LBB0_76
	s_and_b64 vcc, exec, s[10:11]
	s_cbranch_vccz .LBB0_79
	s_barrier

.LBB0_105:
	s_add_u32 s26, s24, 0xfffc0080
	s_addc_u32 s27, s25, -1
	s_add_i32 s55, 0, 0x10000
	s_cmp_eq_u32 s54, 12
	s_cselect_b32 s29, s4, s27
	s_cselect_b32 s28, s5, s26
	v_add_u32_e32 v142, s55, v146
	s_cselect_b32 s27, s15, s51
	s_cselect_b32 s26, s17, s50
	s_add_i32 s57, 0, 0x14000
	ds_read_b128 v[148:151], v142
	ds_read_b128 v[152:155], v142 offset:1024
	ds_read_b128 v[156:159], v142 offset:2048
	ds_read_b128 v[160:163], v142 offset:3072
	v_add_u32_e32 v142, s57, v146
	ds_read_b128 v[164:167], v142
	ds_read_b128 v[168:171], v142 offset:1024
	ds_read_b128 v[172:175], v142 offset:2048
	ds_read_b128 v[176:179], v142 offset:3072
	v_lshl_add_u64 v[142:143], s[24:25], 0, v[138:139]
	s_add_i32 m0, s1, 0xc000
	ds_read_b128 v[188:191], v147
	ds_read_b128 v[192:195], v147 offset:1024
	ds_read_b128 v[196:199], v147 offset:2048
	ds_read_b128 v[200:203], v147 offset:3072
	ds_read_b128 v[204:207], v147 offset:4096
	ds_read_b128 v[208:211], v147 offset:5120
	ds_read_b128 v[212:215], v147 offset:6144
	ds_read_b128 v[216:219], v147 offset:7168
	global_load_lds_dwordx4 v[142:143], off
	v_lshl_add_u64 v[142:143], s[24:25], 0, v[140:141]
	s_add_i32 m0, s1, 0xe000
	s_nop 0
	global_load_lds_dwordx4 v[142:143], off
	s_waitcnt vmcnt(8)
	s_waitcnt lgkmcnt(0)
	s_barrier
	s_waitcnt lgkmcnt(0)
	v_mfma_f32_16x16x32_bf16 v[128:131], v[148:151], v[188:191], v[128:131]
	v_mfma_f32_16x16x32_bf16 v[124:127], v[156:159], v[188:191], v[124:127]
	v_mfma_f32_16x16x32_bf16 v[112:115], v[148:151], v[196:199], v[112:115]
	v_mfma_f32_16x16x32_bf16 v[108:111], v[156:159], v[196:199], v[108:111]
	v_mfma_f32_16x16x32_bf16 v[96:99], v[148:151], v[204:207], v[96:99]
	v_mfma_f32_16x16x32_bf16 v[92:95], v[156:159], v[204:207], v[92:95]
	v_mfma_f32_16x16x32_bf16 v[80:83], v[148:151], v[212:215], v[80:83]
	v_mfma_f32_16x16x32_bf16 v[76:79], v[156:159], v[212:215], v[76:79]
	v_mfma_f32_16x16x32_bf16 v[128:131], v[152:155], v[192:195], v[128:131]
	v_mfma_f32_16x16x32_bf16 v[124:127], v[160:163], v[192:195], v[124:127]
	v_mfma_f32_16x16x32_bf16 v[112:115], v[152:155], v[200:203], v[112:115]
	v_mfma_f32_16x16x32_bf16 v[108:111], v[160:163], v[200:203], v[108:111]
	v_mfma_f32_16x16x32_bf16 v[96:99], v[152:155], v[208:211], v[96:99]
	v_mfma_f32_16x16x32_bf16 v[92:95], v[160:163], v[208:211], v[92:95]
	v_mfma_f32_16x16x32_bf16 v[80:83], v[152:155], v[216:219], v[80:83]
	v_mfma_f32_16x16x32_bf16 v[76:79], v[160:163], v[216:219], v[76:79]
	v_mfma_f32_16x16x32_bf16 v[120:123], v[164:167], v[188:191], v[120:123]
	v_mfma_f32_16x16x32_bf16 v[116:119], v[172:175], v[188:191], v[116:119]
	v_mfma_f32_16x16x32_bf16 v[104:107], v[164:167], v[196:199], v[104:107]
	v_mfma_f32_16x16x32_bf16 v[100:103], v[172:175], v[196:199], v[100:103]
	v_mfma_f32_16x16x32_bf16 v[88:91], v[164:167], v[204:207], v[88:91]
	v_mfma_f32_16x16x32_bf16 v[84:87], v[172:175], v[204:207], v[84:87]
	v_mfma_f32_16x16x32_bf16 v[72:75], v[164:167], v[212:215], v[72:75]
	v_mfma_f32_16x16x32_bf16 v[68:71], v[172:175], v[212:215], v[68:71]
	v_mfma_f32_16x16x32_bf16 v[120:123], v[168:171], v[192:195], v[120:123]
	v_mfma_f32_16x16x32_bf16 v[116:119], v[176:179], v[192:195], v[116:119]
	v_mfma_f32_16x16x32_bf16 v[104:107], v[168:171], v[200:203], v[104:107]
	v_mfma_f32_16x16x32_bf16 v[100:103], v[176:179], v[200:203], v[100:103]
	v_mfma_f32_16x16x32_bf16 v[88:91], v[168:171], v[208:211], v[88:91]
	v_mfma_f32_16x16x32_bf16 v[84:87], v[176:179], v[208:211], v[84:87]
	v_mfma_f32_16x16x32_bf16 v[72:75], v[168:171], v[216:219], v[72:75]
	v_mfma_f32_16x16x32_bf16 v[68:71], v[176:179], v[216:219], v[68:71]
	s_barrier
	s_add_i32 s55, s55, s35
	v_lshl_add_u64 v[142:143], s[26:27], 0, v[180:181]
	s_mov_b32 m0, s55
	ds_read_b128 v[188:191], v147 offset:16384
	ds_read_b128 v[192:195], v147 offset:17408
	ds_read_b128 v[196:199], v147 offset:18432
	ds_read_b128 v[200:203], v147 offset:19456
	ds_read_b128 v[204:207], v147 offset:20480
	ds_read_b128 v[208:211], v147 offset:21504
	ds_read_b128 v[212:215], v147 offset:22528
	ds_read_b128 v[216:219], v147 offset:23552
	global_load_lds_dwordx4 v[142:143], off
	s_add_i32 m0, s55, 0x2000
	s_add_u32 s58, s26, 0x40000
	v_lshl_add_u64 v[220:221], s[26:27], 0, v[132:133]
	s_addc_u32 s59, s27, 0
	s_add_i32 s55, s57, s35
	global_load_lds_dwordx4 v[220:221], off
	v_lshl_add_u64 v[222:223], s[58:59], 0, v[180:181]
	s_mov_b32 m0, s55
	v_lshl_add_u64 v[224:225], s[28:29], 0, v[134:135]
	global_load_lds_dwordx4 v[222:223], off
	v_lshl_add_u64 v[222:223], s[58:59], 0, v[132:133]
	s_add_i32 m0, s55, 0x2000
	s_nop 0
	global_load_lds_dwordx4 v[222:223], off
	v_lshl_add_u64 v[222:223], s[28:29], 0, v[136:137]
	s_mov_b32 m0, s1
	s_nop 0
	global_load_lds_dwordx4 v[222:223], off
	s_mov_b32 m0, s23
	s_nop 0
	global_load_lds_dwordx4 v[224:225], off
	s_waitcnt vmcnt(8)
	s_waitcnt lgkmcnt(0)
	s_barrier
	s_waitcnt lgkmcnt(0)
	v_mfma_f32_16x16x32_bf16 v[64:67], v[148:151], v[188:191], v[64:67]
	v_mfma_f32_16x16x32_bf16 v[60:63], v[156:159], v[188:191], v[60:63]
	v_mfma_f32_16x16x32_bf16 v[48:51], v[148:151], v[196:199], v[48:51]
	v_mfma_f32_16x16x32_bf16 v[44:47], v[156:159], v[196:199], v[44:47]
	v_mfma_f32_16x16x32_bf16 v[32:35], v[148:151], v[204:207], v[32:35]
	v_mfma_f32_16x16x32_bf16 v[28:31], v[156:159], v[204:207], v[28:31]
	v_mfma_f32_16x16x32_bf16 v[16:19], v[148:151], v[212:215], v[16:19]
	v_mfma_f32_16x16x32_bf16 v[12:15], v[156:159], v[212:215], v[12:15]
	v_mfma_f32_16x16x32_bf16 v[64:67], v[152:155], v[192:195], v[64:67]
	v_mfma_f32_16x16x32_bf16 v[60:63], v[160:163], v[192:195], v[60:63]
	v_mfma_f32_16x16x32_bf16 v[48:51], v[152:155], v[200:203], v[48:51]
	v_mfma_f32_16x16x32_bf16 v[44:47], v[160:163], v[200:203], v[44:47]
	v_mfma_f32_16x16x32_bf16 v[32:35], v[152:155], v[208:211], v[32:35]
	v_mfma_f32_16x16x32_bf16 v[28:31], v[160:163], v[208:211], v[28:31]
	v_mfma_f32_16x16x32_bf16 v[16:19], v[152:155], v[216:219], v[16:19]
	v_mfma_f32_16x16x32_bf16 v[12:15], v[160:163], v[216:219], v[12:15]
	v_mfma_f32_16x16x32_bf16 v[56:59], v[164:167], v[188:191], v[56:59]
	v_mfma_f32_16x16x32_bf16 v[52:55], v[172:175], v[188:191], v[52:55]
	v_mfma_f32_16x16x32_bf16 v[40:43], v[164:167], v[196:199], v[40:43]
	v_mfma_f32_16x16x32_bf16 v[36:39], v[172:175], v[196:199], v[36:39]
	v_mfma_f32_16x16x32_bf16 v[24:27], v[164:167], v[204:207], v[24:27]
	v_mfma_f32_16x16x32_bf16 v[20:23], v[172:175], v[204:207], v[20:23]
	v_mfma_f32_16x16x32_bf16 v[8:11], v[164:167], v[212:215], v[8:11]
	v_mfma_f32_16x16x32_bf16 v[4:7], v[172:175], v[212:215], v[4:7]
	v_mfma_f32_16x16x32_bf16 v[56:59], v[168:171], v[192:195], v[56:59]
	v_mfma_f32_16x16x32_bf16 v[52:55], v[176:179], v[192:195], v[52:55]
	v_mfma_f32_16x16x32_bf16 v[40:43], v[168:171], v[200:203], v[40:43]
	v_mfma_f32_16x16x32_bf16 v[36:39], v[176:179], v[200:203], v[36:39]
	v_mfma_f32_16x16x32_bf16 v[24:27], v[168:171], v[208:211], v[24:27]
	v_mfma_f32_16x16x32_bf16 v[20:23], v[176:179], v[208:211], v[20:23]
	v_mfma_f32_16x16x32_bf16 v[8:11], v[168:171], v[216:219], v[8:11]
	v_mfma_f32_16x16x32_bf16 v[4:7], v[176:179], v[216:219], v[4:7]
	s_barrier
	s_add_i32 s55, 0, 0x18000
	s_add_i32 s57, 0, 0x1c000
	v_add_u32_e32 v160, s55, v146
	v_add_u32_e32 v176, s57, v146
	ds_read_b128 v[148:151], v160
	ds_read_b128 v[152:155], v160 offset:1024
	ds_read_b128 v[156:159], v160 offset:2048
	ds_read_b128 v[160:163], v160 offset:3072
	ds_read_b128 v[164:167], v176
	ds_read_b128 v[168:171], v176 offset:1024
	ds_read_b128 v[172:175], v176 offset:2048
	ds_read_b128 v[176:179], v176 offset:3072
	s_add_u32 s28, s28, 0x40000
	s_addc_u32 s29, s29, 0
	s_mov_b32 m0, s38
	v_lshl_add_u64 v[226:227], s[28:29], 0, v[136:137]
	ds_read_b128 v[188:191], v147 offset:32768
	ds_read_b128 v[192:195], v147 offset:33792
	ds_read_b128 v[196:199], v147 offset:34816
	ds_read_b128 v[200:203], v147 offset:35840
	ds_read_b128 v[204:207], v147 offset:36864
	ds_read_b128 v[208:211], v147 offset:37888
	ds_read_b128 v[212:215], v147 offset:38912
	ds_read_b128 v[216:219], v147 offset:39936
	global_load_lds_dwordx4 v[226:227], off
	v_lshl_add_u64 v[226:227], s[28:29], 0, v[134:135]
	s_mov_b32 m0, s39
	s_nop 0
	global_load_lds_dwordx4 v[226:227], off
	s_waitcnt vmcnt(8)
	s_waitcnt lgkmcnt(0)
	s_barrier
	s_waitcnt lgkmcnt(0)
	v_mfma_f32_16x16x32_bf16 v[128:131], v[148:151], v[188:191], v[128:131]
	v_mfma_f32_16x16x32_bf16 v[124:127], v[156:159], v[188:191], v[124:127]
	v_mfma_f32_16x16x32_bf16 v[112:115], v[148:151], v[196:199], v[112:115]
	v_mfma_f32_16x16x32_bf16 v[108:111], v[156:159], v[196:199], v[108:111]
	v_mfma_f32_16x16x32_bf16 v[96:99], v[148:151], v[204:207], v[96:99]
	v_mfma_f32_16x16x32_bf16 v[92:95], v[156:159], v[204:207], v[92:95]
	v_mfma_f32_16x16x32_bf16 v[80:83], v[148:151], v[212:215], v[80:83]
	v_mfma_f32_16x16x32_bf16 v[76:79], v[156:159], v[212:215], v[76:79]
	v_mfma_f32_16x16x32_bf16 v[128:131], v[152:155], v[192:195], v[128:131]
	v_mfma_f32_16x16x32_bf16 v[124:127], v[160:163], v[192:195], v[124:127]
	v_mfma_f32_16x16x32_bf16 v[112:115], v[152:155], v[200:203], v[112:115]
	v_mfma_f32_16x16x32_bf16 v[108:111], v[160:163], v[200:203], v[108:111]
	v_mfma_f32_16x16x32_bf16 v[96:99], v[152:155], v[208:211], v[96:99]
	v_mfma_f32_16x16x32_bf16 v[92:95], v[160:163], v[208:211], v[92:95]
	v_mfma_f32_16x16x32_bf16 v[80:83], v[152:155], v[216:219], v[80:83]
	v_mfma_f32_16x16x32_bf16 v[76:79], v[160:163], v[216:219], v[76:79]
	v_mfma_f32_16x16x32_bf16 v[120:123], v[164:167], v[188:191], v[120:123]
	v_mfma_f32_16x16x32_bf16 v[116:119], v[172:175], v[188:191], v[116:119]
	v_mfma_f32_16x16x32_bf16 v[104:107], v[164:167], v[196:199], v[104:107]
	v_mfma_f32_16x16x32_bf16 v[100:103], v[172:175], v[196:199], v[100:103]
	v_mfma_f32_16x16x32_bf16 v[88:91], v[164:167], v[204:207], v[88:91]
	v_mfma_f32_16x16x32_bf16 v[84:87], v[172:175], v[204:207], v[84:87]
	v_mfma_f32_16x16x32_bf16 v[72:75], v[164:167], v[212:215], v[72:75]
	v_mfma_f32_16x16x32_bf16 v[68:71], v[172:175], v[212:215], v[68:71]
	v_mfma_f32_16x16x32_bf16 v[120:123], v[168:171], v[192:195], v[120:123]
	v_mfma_f32_16x16x32_bf16 v[116:119], v[176:179], v[192:195], v[116:119]
	v_mfma_f32_16x16x32_bf16 v[104:107], v[168:171], v[200:203], v[104:107]
	v_mfma_f32_16x16x32_bf16 v[100:103], v[176:179], v[200:203], v[100:103]
	v_mfma_f32_16x16x32_bf16 v[88:91], v[168:171], v[208:211], v[88:91]
	v_mfma_f32_16x16x32_bf16 v[84:87], v[176:179], v[208:211], v[84:87]
	v_mfma_f32_16x16x32_bf16 v[72:75], v[168:171], v[216:219], v[72:75]
	v_mfma_f32_16x16x32_bf16 v[68:71], v[176:179], v[216:219], v[68:71]
	s_barrier
	s_add_i32 s28, s55, s35
	v_lshl_add_u64 v[142:143], v[142:143], 0, s[52:53]
	s_mov_b32 m0, s28
	ds_read_b128 v[188:191], v147 offset:49152
	ds_read_b128 v[192:195], v147 offset:50176
	ds_read_b128 v[196:199], v147 offset:51200
	ds_read_b128 v[200:203], v147 offset:52224
	ds_read_b128 v[204:207], v147 offset:53248
	ds_read_b128 v[208:211], v147 offset:54272
	ds_read_b128 v[212:215], v147 offset:55296
	ds_read_b128 v[216:219], v147 offset:56320
	global_load_lds_dwordx4 v[142:143], off
	s_add_i32 m0, s28, 0x2000
	s_add_u32 s26, s26, 0x40080
	v_lshl_add_u64 v[142:143], v[220:221], 0, s[52:53]
	s_addc_u32 s27, s27, 0
	s_add_i32 s28, s57, s35
	global_load_lds_dwordx4 v[142:143], off
	v_lshl_add_u64 v[142:143], s[26:27], 0, v[180:181]
	s_mov_b32 m0, s28
	s_nop 0
	global_load_lds_dwordx4 v[142:143], off
	v_lshl_add_u64 v[142:143], s[26:27], 0, v[132:133]
	s_add_i32 m0, s28, 0x2000
	s_nop 0
	global_load_lds_dwordx4 v[142:143], off
	v_lshl_add_u64 v[142:143], v[222:223], 0, s[52:53]
	s_mov_b32 m0, s42
	s_nop 0
	global_load_lds_dwordx4 v[142:143], off
	v_lshl_add_u64 v[142:143], v[224:225], 0, s[52:53]
	s_mov_b32 m0, s43
	s_nop 0
	global_load_lds_dwordx4 v[142:143], off
	s_waitcnt vmcnt(8)
	s_waitcnt lgkmcnt(0)
	s_barrier
	s_waitcnt lgkmcnt(0)
	v_mfma_f32_16x16x32_bf16 v[64:67], v[148:151], v[188:191], v[64:67]
	v_mfma_f32_16x16x32_bf16 v[60:63], v[156:159], v[188:191], v[60:63]
	v_mfma_f32_16x16x32_bf16 v[48:51], v[148:151], v[196:199], v[48:51]
	v_mfma_f32_16x16x32_bf16 v[44:47], v[156:159], v[196:199], v[44:47]
	v_mfma_f32_16x16x32_bf16 v[32:35], v[148:151], v[204:207], v[32:35]
	v_mfma_f32_16x16x32_bf16 v[28:31], v[156:159], v[204:207], v[28:31]
	v_mfma_f32_16x16x32_bf16 v[16:19], v[148:151], v[212:215], v[16:19]
	v_mfma_f32_16x16x32_bf16 v[12:15], v[156:159], v[212:215], v[12:15]
	v_mfma_f32_16x16x32_bf16 v[64:67], v[152:155], v[192:195], v[64:67]
	v_mfma_f32_16x16x32_bf16 v[60:63], v[160:163], v[192:195], v[60:63]
	v_mfma_f32_16x16x32_bf16 v[48:51], v[152:155], v[200:203], v[48:51]
	v_mfma_f32_16x16x32_bf16 v[44:47], v[160:163], v[200:203], v[44:47]
	v_mfma_f32_16x16x32_bf16 v[32:35], v[152:155], v[208:211], v[32:35]
	v_mfma_f32_16x16x32_bf16 v[28:31], v[160:163], v[208:211], v[28:31]
	v_mfma_f32_16x16x32_bf16 v[16:19], v[152:155], v[216:219], v[16:19]
	v_mfma_f32_16x16x32_bf16 v[12:15], v[160:163], v[216:219], v[12:15]
	v_mfma_f32_16x16x32_bf16 v[56:59], v[164:167], v[188:191], v[56:59]
	v_mfma_f32_16x16x32_bf16 v[52:55], v[172:175], v[188:191], v[52:55]
	v_mfma_f32_16x16x32_bf16 v[40:43], v[164:167], v[196:199], v[40:43]
	v_mfma_f32_16x16x32_bf16 v[36:39], v[172:175], v[196:199], v[36:39]
	v_mfma_f32_16x16x32_bf16 v[24:27], v[164:167], v[204:207], v[24:27]
	v_mfma_f32_16x16x32_bf16 v[20:23], v[172:175], v[204:207], v[20:23]
	v_mfma_f32_16x16x32_bf16 v[8:11], v[164:167], v[212:215], v[8:11]
	v_mfma_f32_16x16x32_bf16 v[4:7], v[172:175], v[212:215], v[4:7]
	v_mfma_f32_16x16x32_bf16 v[56:59], v[168:171], v[192:195], v[56:59]
	v_mfma_f32_16x16x32_bf16 v[52:55], v[176:179], v[192:195], v[52:55]
	v_mfma_f32_16x16x32_bf16 v[40:43], v[168:171], v[200:203], v[40:43]
	v_mfma_f32_16x16x32_bf16 v[36:39], v[176:179], v[200:203], v[36:39]
	v_mfma_f32_16x16x32_bf16 v[24:27], v[168:171], v[208:211], v[24:27]
	v_mfma_f32_16x16x32_bf16 v[20:23], v[176:179], v[208:211], v[20:23]
	v_mfma_f32_16x16x32_bf16 v[8:11], v[168:171], v[216:219], v[8:11]
	v_mfma_f32_16x16x32_bf16 v[4:7], v[176:179], v[216:219], v[4:7]
	s_barrier
	s_add_i32 s54, s54, 2
	s_add_u32 s24, s24, 0x100
	s_addc_u32 s25, s25, 0
	s_add_u32 s50, s50, 0x100
	s_addc_u32 s51, s51, 0
	s_cmp_gt_u32 s54, 13
	s_cbranch_scc0 .LBB0_105
	s_and_b64 vcc, exec, s[12:13]
	s_cbranch_vccz .LBB0_108
	s_barrier

.LBB0_255:
	s_add_u32 s30, s28, 0xfffc0080
	s_addc_u32 s31, s29, -1
	s_add_i32 s33, 0, 0x10000
	s_cmp_eq_u32 s27, 12
	s_cselect_b32 s35, s1, s31
	s_cselect_b32 s34, s2, s30
	s_cselect_b32 s31, s4, s21
	s_cselect_b32 s30, s5, s19
	s_add_i32 s47, 0, 0x14000
	v_add_u32_e32 v80, s33, v212
	v_add_u32_e32 v166, s47, v212
	ds_read_b128 v[68:71], v80
	ds_read_b128 v[72:75], v80 offset:1024
	ds_read_b128 v[76:79], v80 offset:2048
	ds_read_b128 v[80:83], v80 offset:3072
	ds_read_b128 v[148:151], v166
	ds_read_b128 v[158:161], v166 offset:1024
	ds_read_b128 v[162:165], v166 offset:2048
	ds_read_b128 v[166:169], v166 offset:3072
	v_lshl_add_u64 v[178:179], s[28:29], 0, v[154:155]
	s_add_i32 m0, s56, 0xc000
	ds_read_b128 v[170:173], v213
	ds_read_b128 v[174:177], v213 offset:1024
	ds_read_b128 v[188:191], v213 offset:2048
	ds_read_b128 v[192:195], v213 offset:3072
	ds_read_b128 v[196:199], v213 offset:4096
	ds_read_b128 v[200:203], v213 offset:5120
	ds_read_b128 v[204:207], v213 offset:6144
	ds_read_b128 v[208:211], v213 offset:7168
	global_load_lds_dwordx4 v[178:179], off
	v_lshl_add_u64 v[178:179], s[28:29], 0, v[156:157]
	s_add_i32 m0, s56, 0xe000
	s_nop 0
	global_load_lds_dwordx4 v[178:179], off
	s_waitcnt vmcnt(8)
	s_waitcnt lgkmcnt(0)
	s_barrier
	s_waitcnt lgkmcnt(0)
	v_mfma_f32_16x16x32_bf16 v[144:147], v[68:71], v[170:173], v[144:147]
	v_mfma_f32_16x16x32_bf16 v[140:143], v[76:79], v[170:173], v[140:143]
	v_mfma_f32_16x16x32_bf16 v[136:139], v[68:71], v[188:191], v[136:139]
	v_mfma_f32_16x16x32_bf16 v[132:135], v[76:79], v[188:191], v[132:135]
	v_mfma_f32_16x16x32_bf16 v[112:115], v[68:71], v[196:199], v[112:115]
	v_mfma_f32_16x16x32_bf16 v[108:111], v[76:79], v[196:199], v[108:111]
	v_mfma_f32_16x16x32_bf16 v[104:107], v[68:71], v[204:207], v[104:107]
	v_mfma_f32_16x16x32_bf16 v[100:103], v[76:79], v[204:207], v[100:103]
	v_mfma_f32_16x16x32_bf16 v[144:147], v[72:75], v[174:177], v[144:147]
	v_mfma_f32_16x16x32_bf16 v[140:143], v[80:83], v[174:177], v[140:143]
	v_mfma_f32_16x16x32_bf16 v[136:139], v[72:75], v[192:195], v[136:139]
	v_mfma_f32_16x16x32_bf16 v[132:135], v[80:83], v[192:195], v[132:135]
	v_mfma_f32_16x16x32_bf16 v[112:115], v[72:75], v[200:203], v[112:115]
	v_mfma_f32_16x16x32_bf16 v[108:111], v[80:83], v[200:203], v[108:111]
	v_mfma_f32_16x16x32_bf16 v[104:107], v[72:75], v[208:211], v[104:107]
	v_mfma_f32_16x16x32_bf16 v[100:103], v[80:83], v[208:211], v[100:103]
	v_mfma_f32_16x16x32_bf16 v[128:131], v[148:151], v[170:173], v[128:131]
	v_mfma_f32_16x16x32_bf16 v[124:127], v[162:165], v[170:173], v[124:127]
	v_mfma_f32_16x16x32_bf16 v[120:123], v[148:151], v[188:191], v[120:123]
	v_mfma_f32_16x16x32_bf16 v[116:119], v[162:165], v[188:191], v[116:119]
	v_mfma_f32_16x16x32_bf16 v[96:99], v[148:151], v[196:199], v[96:99]
	v_mfma_f32_16x16x32_bf16 v[92:95], v[162:165], v[196:199], v[92:95]
	v_mfma_f32_16x16x32_bf16 v[88:91], v[148:151], v[204:207], v[88:91]
	v_mfma_f32_16x16x32_bf16 v[84:87], v[162:165], v[204:207], v[84:87]
	v_mfma_f32_16x16x32_bf16 v[128:131], v[158:161], v[174:177], v[128:131]
	v_mfma_f32_16x16x32_bf16 v[124:127], v[166:169], v[174:177], v[124:127]
	v_mfma_f32_16x16x32_bf16 v[120:123], v[158:161], v[192:195], v[120:123]
	v_mfma_f32_16x16x32_bf16 v[116:119], v[166:169], v[192:195], v[116:119]
	v_mfma_f32_16x16x32_bf16 v[96:99], v[158:161], v[200:203], v[96:99]
	v_mfma_f32_16x16x32_bf16 v[92:95], v[166:169], v[200:203], v[92:95]
	v_mfma_f32_16x16x32_bf16 v[88:91], v[158:161], v[208:211], v[88:91]
	v_mfma_f32_16x16x32_bf16 v[84:87], v[166:169], v[208:211], v[84:87]
	s_barrier
	s_add_i32 s33, s33, s43
	v_lshl_add_u64 v[178:179], s[30:31], 0, v[180:181]
	s_mov_b32 m0, s33
	ds_read_b128 v[170:173], v213 offset:16384
	ds_read_b128 v[174:177], v213 offset:17408
	ds_read_b128 v[188:191], v213 offset:18432
	ds_read_b128 v[192:195], v213 offset:19456
	ds_read_b128 v[196:199], v213 offset:20480
	ds_read_b128 v[200:203], v213 offset:21504
	ds_read_b128 v[204:207], v213 offset:22528
	ds_read_b128 v[208:211], v213 offset:23552
	global_load_lds_dwordx4 v[178:179], off
	s_add_i32 m0, s33, 0x2000
	s_add_u32 s44, s30, 0x40000
	v_lshl_add_u64 v[214:215], s[30:31], 0, v[152:153]
	s_addc_u32 s45, s31, 0
	s_add_i32 s33, s47, s43
	global_load_lds_dwordx4 v[214:215], off
	v_lshl_add_u64 v[216:217], s[44:45], 0, v[180:181]
	s_mov_b32 m0, s33
	v_lshl_add_u64 v[218:219], s[34:35], 0, v[152:153]
	global_load_lds_dwordx4 v[216:217], off
	v_lshl_add_u64 v[216:217], s[44:45], 0, v[152:153]
	s_add_i32 m0, s33, 0x2000
	s_nop 0
	global_load_lds_dwordx4 v[216:217], off
	v_lshl_add_u64 v[216:217], s[34:35], 0, v[180:181]
	s_mov_b32 m0, s56
	s_nop 0
	global_load_lds_dwordx4 v[216:217], off
	s_mov_b32 m0, s57
	s_nop 0
	global_load_lds_dwordx4 v[218:219], off
	s_waitcnt vmcnt(8)
	s_waitcnt lgkmcnt(0)
	s_barrier
	s_waitcnt lgkmcnt(0)
	v_mfma_f32_16x16x32_bf16 v[64:67], v[68:71], v[170:173], v[64:67]
	v_mfma_f32_16x16x32_bf16 v[60:63], v[76:79], v[170:173], v[60:63]
	v_mfma_f32_16x16x32_bf16 v[56:59], v[68:71], v[188:191], v[56:59]
	v_mfma_f32_16x16x32_bf16 v[52:55], v[76:79], v[188:191], v[52:55]
	v_mfma_f32_16x16x32_bf16 v[32:35], v[68:71], v[196:199], v[32:35]
	v_mfma_f32_16x16x32_bf16 v[28:31], v[76:79], v[196:199], v[28:31]
	v_mfma_f32_16x16x32_bf16 v[16:19], v[68:71], v[204:207], v[16:19]
	v_mfma_f32_16x16x32_bf16 v[12:15], v[76:79], v[204:207], v[12:15]
	v_mfma_f32_16x16x32_bf16 v[64:67], v[72:75], v[174:177], v[64:67]
	v_mfma_f32_16x16x32_bf16 v[60:63], v[80:83], v[174:177], v[60:63]
	v_mfma_f32_16x16x32_bf16 v[56:59], v[72:75], v[192:195], v[56:59]
	v_mfma_f32_16x16x32_bf16 v[52:55], v[80:83], v[192:195], v[52:55]
	v_mfma_f32_16x16x32_bf16 v[32:35], v[72:75], v[200:203], v[32:35]
	v_mfma_f32_16x16x32_bf16 v[28:31], v[80:83], v[200:203], v[28:31]
	v_mfma_f32_16x16x32_bf16 v[16:19], v[72:75], v[208:211], v[16:19]
	v_mfma_f32_16x16x32_bf16 v[12:15], v[80:83], v[208:211], v[12:15]
	v_mfma_f32_16x16x32_bf16 v[48:51], v[148:151], v[170:173], v[48:51]
	v_mfma_f32_16x16x32_bf16 v[44:47], v[162:165], v[170:173], v[44:47]
	v_mfma_f32_16x16x32_bf16 v[40:43], v[148:151], v[188:191], v[40:43]
	v_mfma_f32_16x16x32_bf16 v[36:39], v[162:165], v[188:191], v[36:39]
	v_mfma_f32_16x16x32_bf16 v[24:27], v[148:151], v[196:199], v[24:27]
	v_mfma_f32_16x16x32_bf16 v[20:23], v[162:165], v[196:199], v[20:23]
	v_mfma_f32_16x16x32_bf16 v[8:11], v[148:151], v[204:207], v[8:11]
	v_mfma_f32_16x16x32_bf16 v[4:7], v[162:165], v[204:207], v[4:7]
	v_mfma_f32_16x16x32_bf16 v[48:51], v[158:161], v[174:177], v[48:51]
	v_mfma_f32_16x16x32_bf16 v[44:47], v[166:169], v[174:177], v[44:47]
	v_mfma_f32_16x16x32_bf16 v[40:43], v[158:161], v[192:195], v[40:43]
	v_mfma_f32_16x16x32_bf16 v[36:39], v[166:169], v[192:195], v[36:39]
	v_mfma_f32_16x16x32_bf16 v[24:27], v[158:161], v[200:203], v[24:27]
	v_mfma_f32_16x16x32_bf16 v[20:23], v[166:169], v[200:203], v[20:23]
	v_mfma_f32_16x16x32_bf16 v[8:11], v[158:161], v[208:211], v[8:11]
	v_mfma_f32_16x16x32_bf16 v[4:7], v[166:169], v[208:211], v[4:7]
	s_barrier
	s_add_i32 s33, 0, 0x18000
	s_add_i32 s44, 0, 0x1c000
	v_add_u32_e32 v80, s33, v212
	v_add_u32_e32 v166, s44, v212
	ds_read_b128 v[68:71], v80
	ds_read_b128 v[72:75], v80 offset:1024
	ds_read_b128 v[76:79], v80 offset:2048
	ds_read_b128 v[80:83], v80 offset:3072
	ds_read_b128 v[148:151], v166
	ds_read_b128 v[158:161], v166 offset:1024
	ds_read_b128 v[162:165], v166 offset:2048
	ds_read_b128 v[166:169], v166 offset:3072
	s_add_u32 s34, s34, 0x40000
	s_addc_u32 s35, s35, 0
	s_mov_b32 m0, s58
	v_lshl_add_u64 v[220:221], s[34:35], 0, v[180:181]
	ds_read_b128 v[170:173], v213 offset:32768
	ds_read_b128 v[174:177], v213 offset:33792
	ds_read_b128 v[188:191], v213 offset:34816
	ds_read_b128 v[192:195], v213 offset:35840
	ds_read_b128 v[196:199], v213 offset:36864
	ds_read_b128 v[200:203], v213 offset:37888
	ds_read_b128 v[204:207], v213 offset:38912
	ds_read_b128 v[208:211], v213 offset:39936
	global_load_lds_dwordx4 v[220:221], off
	v_lshl_add_u64 v[220:221], s[34:35], 0, v[152:153]
	s_mov_b32 m0, s59
	s_nop 0
	global_load_lds_dwordx4 v[220:221], off
	s_waitcnt vmcnt(8)
	s_waitcnt lgkmcnt(0)
	s_barrier
	s_waitcnt lgkmcnt(0)
	v_mfma_f32_16x16x32_bf16 v[144:147], v[68:71], v[170:173], v[144:147]
	v_mfma_f32_16x16x32_bf16 v[140:143], v[76:79], v[170:173], v[140:143]
	v_mfma_f32_16x16x32_bf16 v[136:139], v[68:71], v[188:191], v[136:139]
	v_mfma_f32_16x16x32_bf16 v[132:135], v[76:79], v[188:191], v[132:135]
	v_mfma_f32_16x16x32_bf16 v[112:115], v[68:71], v[196:199], v[112:115]
	v_mfma_f32_16x16x32_bf16 v[108:111], v[76:79], v[196:199], v[108:111]
	v_mfma_f32_16x16x32_bf16 v[104:107], v[68:71], v[204:207], v[104:107]
	v_mfma_f32_16x16x32_bf16 v[100:103], v[76:79], v[204:207], v[100:103]
	v_mfma_f32_16x16x32_bf16 v[144:147], v[72:75], v[174:177], v[144:147]
	v_mfma_f32_16x16x32_bf16 v[140:143], v[80:83], v[174:177], v[140:143]
	v_mfma_f32_16x16x32_bf16 v[136:139], v[72:75], v[192:195], v[136:139]
	v_mfma_f32_16x16x32_bf16 v[132:135], v[80:83], v[192:195], v[132:135]
	v_mfma_f32_16x16x32_bf16 v[112:115], v[72:75], v[200:203], v[112:115]
	v_mfma_f32_16x16x32_bf16 v[108:111], v[80:83], v[200:203], v[108:111]
	v_mfma_f32_16x16x32_bf16 v[104:107], v[72:75], v[208:211], v[104:107]
	v_mfma_f32_16x16x32_bf16 v[100:103], v[80:83], v[208:211], v[100:103]
	v_mfma_f32_16x16x32_bf16 v[128:131], v[148:151], v[170:173], v[128:131]
	v_mfma_f32_16x16x32_bf16 v[124:127], v[162:165], v[170:173], v[124:127]
	v_mfma_f32_16x16x32_bf16 v[120:123], v[148:151], v[188:191], v[120:123]
	v_mfma_f32_16x16x32_bf16 v[116:119], v[162:165], v[188:191], v[116:119]
	v_mfma_f32_16x16x32_bf16 v[96:99], v[148:151], v[196:199], v[96:99]
	v_mfma_f32_16x16x32_bf16 v[92:95], v[162:165], v[196:199], v[92:95]
	v_mfma_f32_16x16x32_bf16 v[88:91], v[148:151], v[204:207], v[88:91]
	v_mfma_f32_16x16x32_bf16 v[84:87], v[162:165], v[204:207], v[84:87]
	v_mfma_f32_16x16x32_bf16 v[128:131], v[158:161], v[174:177], v[128:131]
	v_mfma_f32_16x16x32_bf16 v[124:127], v[166:169], v[174:177], v[124:127]
	v_mfma_f32_16x16x32_bf16 v[120:123], v[158:161], v[192:195], v[120:123]
	v_mfma_f32_16x16x32_bf16 v[116:119], v[166:169], v[192:195], v[116:119]
	v_mfma_f32_16x16x32_bf16 v[96:99], v[158:161], v[200:203], v[96:99]
	v_mfma_f32_16x16x32_bf16 v[92:95], v[166:169], v[200:203], v[92:95]
	v_mfma_f32_16x16x32_bf16 v[88:91], v[158:161], v[208:211], v[88:91]
	v_mfma_f32_16x16x32_bf16 v[84:87], v[166:169], v[208:211], v[84:87]
	s_barrier
	s_add_i32 s33, s33, s43
	v_lshl_add_u64 v[178:179], v[178:179], 0, s[52:53]
	s_mov_b32 m0, s33
	ds_read_b128 v[170:173], v213 offset:49152
	ds_read_b128 v[174:177], v213 offset:50176
	ds_read_b128 v[188:191], v213 offset:51200
	ds_read_b128 v[192:195], v213 offset:52224
	ds_read_b128 v[196:199], v213 offset:53248
	ds_read_b128 v[200:203], v213 offset:54272
	ds_read_b128 v[204:207], v213 offset:55296
	ds_read_b128 v[208:211], v213 offset:56320
	global_load_lds_dwordx4 v[178:179], off
	s_add_i32 m0, s33, 0x2000
	s_add_u32 s30, s30, 0x40080
	v_lshl_add_u64 v[178:179], v[214:215], 0, s[52:53]
	s_addc_u32 s31, s31, 0
	s_add_i32 s33, s44, s43
	global_load_lds_dwordx4 v[178:179], off
	v_lshl_add_u64 v[178:179], s[30:31], 0, v[180:181]
	s_mov_b32 m0, s33
	s_nop 0
	global_load_lds_dwordx4 v[178:179], off
	v_lshl_add_u64 v[178:179], s[30:31], 0, v[152:153]
	s_add_i32 m0, s33, 0x2000
	s_nop 0
	global_load_lds_dwordx4 v[178:179], off
	v_lshl_add_u64 v[178:179], v[216:217], 0, s[52:53]
	s_mov_b32 m0, s84
	s_nop 0
	global_load_lds_dwordx4 v[178:179], off
	v_lshl_add_u64 v[178:179], v[218:219], 0, s[52:53]
	s_mov_b32 m0, s85
	s_nop 0
	global_load_lds_dwordx4 v[178:179], off
	s_waitcnt vmcnt(8)
	s_waitcnt lgkmcnt(0)
	s_barrier
	s_waitcnt lgkmcnt(0)
	v_mfma_f32_16x16x32_bf16 v[64:67], v[68:71], v[170:173], v[64:67]
	v_mfma_f32_16x16x32_bf16 v[60:63], v[76:79], v[170:173], v[60:63]
	v_mfma_f32_16x16x32_bf16 v[56:59], v[68:71], v[188:191], v[56:59]
	v_mfma_f32_16x16x32_bf16 v[52:55], v[76:79], v[188:191], v[52:55]
	v_mfma_f32_16x16x32_bf16 v[32:35], v[68:71], v[196:199], v[32:35]
	v_mfma_f32_16x16x32_bf16 v[28:31], v[76:79], v[196:199], v[28:31]
	v_mfma_f32_16x16x32_bf16 v[16:19], v[68:71], v[204:207], v[16:19]
	v_mfma_f32_16x16x32_bf16 v[12:15], v[76:79], v[204:207], v[12:15]
	v_mfma_f32_16x16x32_bf16 v[64:67], v[72:75], v[174:177], v[64:67]
	v_mfma_f32_16x16x32_bf16 v[60:63], v[80:83], v[174:177], v[60:63]
	v_mfma_f32_16x16x32_bf16 v[56:59], v[72:75], v[192:195], v[56:59]
	v_mfma_f32_16x16x32_bf16 v[52:55], v[80:83], v[192:195], v[52:55]
	v_mfma_f32_16x16x32_bf16 v[32:35], v[72:75], v[200:203], v[32:35]
	v_mfma_f32_16x16x32_bf16 v[28:31], v[80:83], v[200:203], v[28:31]
	v_mfma_f32_16x16x32_bf16 v[16:19], v[72:75], v[208:211], v[16:19]
	v_mfma_f32_16x16x32_bf16 v[12:15], v[80:83], v[208:211], v[12:15]
	v_mfma_f32_16x16x32_bf16 v[48:51], v[148:151], v[170:173], v[48:51]
	v_mfma_f32_16x16x32_bf16 v[44:47], v[162:165], v[170:173], v[44:47]
	v_mfma_f32_16x16x32_bf16 v[40:43], v[148:151], v[188:191], v[40:43]
	v_mfma_f32_16x16x32_bf16 v[36:39], v[162:165], v[188:191], v[36:39]
	v_mfma_f32_16x16x32_bf16 v[24:27], v[148:151], v[196:199], v[24:27]
	v_mfma_f32_16x16x32_bf16 v[20:23], v[162:165], v[196:199], v[20:23]
	v_mfma_f32_16x16x32_bf16 v[8:11], v[148:151], v[204:207], v[8:11]
	v_mfma_f32_16x16x32_bf16 v[4:7], v[162:165], v[204:207], v[4:7]
	v_mfma_f32_16x16x32_bf16 v[48:51], v[158:161], v[174:177], v[48:51]
	v_mfma_f32_16x16x32_bf16 v[44:47], v[166:169], v[174:177], v[44:47]
	v_mfma_f32_16x16x32_bf16 v[40:43], v[158:161], v[192:195], v[40:43]
	v_mfma_f32_16x16x32_bf16 v[36:39], v[166:169], v[192:195], v[36:39]
	v_mfma_f32_16x16x32_bf16 v[24:27], v[158:161], v[200:203], v[24:27]
	v_mfma_f32_16x16x32_bf16 v[20:23], v[166:169], v[200:203], v[20:23]
	v_mfma_f32_16x16x32_bf16 v[8:11], v[158:161], v[208:211], v[8:11]
	v_mfma_f32_16x16x32_bf16 v[4:7], v[166:169], v[208:211], v[4:7]
	s_barrier
	s_add_i32 s27, s27, 2
	s_add_u32 s28, s28, 0x100
	s_addc_u32 s29, s29, 0
	s_add_u32 s19, s19, 0x100
	s_addc_u32 s21, s21, 0
	s_cmp_gt_u32 s27, 13
	s_cbranch_scc0 .LBB0_255
	s_and_b64 vcc, exec, s[14:15]
	s_cbranch_vccz .LBB0_258
	s_barrier

.LBB0_300:
	s_add_i32 s33, s31, 2
	s_add_u32 s36, s34, 0xfffc0080
	s_addc_u32 s37, s35, -1
	s_add_i32 s44, 0, 0x10000
	s_cmp_eq_u32 s19, s31
	s_cselect_b32 s39, s2, s37
	s_cselect_b32 s38, s4, s36
	s_cselect_b32 s37, s5, s29
	s_cselect_b32 s36, s17, s21
	s_add_i32 s31, 0, 0x14000
	v_add_u32_e32 v128, s44, v220
	v_add_u32_e32 v160, s31, v220
	ds_read_b128 v[100:103], v128
	ds_read_b128 v[104:107], v128 offset:1024
	ds_read_b128 v[108:111], v128 offset:2048
	ds_read_b128 v[128:131], v128 offset:3072
	ds_read_b128 v[148:151], v160
	ds_read_b128 v[152:155], v160 offset:1024
	ds_read_b128 v[156:159], v160 offset:2048
	ds_read_b128 v[160:163], v160 offset:3072
	v_lshl_add_u64 v[210:211], s[34:35], 0, v[190:191]
	s_add_i32 m0, s51, 0xc000
	ds_read_b128 v[164:167], v221
	ds_read_b128 v[168:171], v221 offset:1024
	ds_read_b128 v[172:175], v221 offset:2048
	ds_read_b128 v[176:179], v221 offset:3072
	ds_read_b128 v[194:197], v221 offset:4096
	ds_read_b128 v[198:201], v221 offset:5120
	ds_read_b128 v[202:205], v221 offset:6144
	ds_read_b128 v[206:209], v221 offset:7168
	global_load_lds_dwordx4 v[210:211], off
	v_lshl_add_u64 v[210:211], s[34:35], 0, v[192:193]
	s_add_i32 m0, s51, 0xe000
	s_nop 0
	global_load_lds_dwordx4 v[210:211], off
	s_waitcnt vmcnt(8)
	s_waitcnt lgkmcnt(0)
	s_barrier
	s_waitcnt lgkmcnt(0)
	v_mfma_f32_16x16x32_bf16 v[144:147], v[100:103], v[164:167], v[144:147]
	v_mfma_f32_16x16x32_bf16 v[140:143], v[108:111], v[164:167], v[140:143]
	v_mfma_f32_16x16x32_bf16 v[136:139], v[100:103], v[172:175], v[136:139]
	v_mfma_f32_16x16x32_bf16 v[132:135], v[108:111], v[172:175], v[132:135]
	v_mfma_f32_16x16x32_bf16 v[96:99], v[100:103], v[194:197], v[96:99]
	v_mfma_f32_16x16x32_bf16 v[92:95], v[108:111], v[194:197], v[92:95]
	v_mfma_f32_16x16x32_bf16 v[88:91], v[100:103], v[202:205], v[88:91]
	v_mfma_f32_16x16x32_bf16 v[84:87], v[108:111], v[202:205], v[84:87]
	v_mfma_f32_16x16x32_bf16 v[144:147], v[104:107], v[168:171], v[144:147]
	v_mfma_f32_16x16x32_bf16 v[140:143], v[128:131], v[168:171], v[140:143]
	v_mfma_f32_16x16x32_bf16 v[136:139], v[104:107], v[176:179], v[136:139]
	v_mfma_f32_16x16x32_bf16 v[132:135], v[128:131], v[176:179], v[132:135]
	v_mfma_f32_16x16x32_bf16 v[96:99], v[104:107], v[198:201], v[96:99]
	v_mfma_f32_16x16x32_bf16 v[92:95], v[128:131], v[198:201], v[92:95]
	v_mfma_f32_16x16x32_bf16 v[88:91], v[104:107], v[206:209], v[88:91]
	v_mfma_f32_16x16x32_bf16 v[84:87], v[128:131], v[206:209], v[84:87]
	v_mfma_f32_16x16x32_bf16 v[124:127], v[148:151], v[164:167], v[124:127]
	v_mfma_f32_16x16x32_bf16 v[120:123], v[156:159], v[164:167], v[120:123]
	v_mfma_f32_16x16x32_bf16 v[116:119], v[148:151], v[172:175], v[116:119]
	v_mfma_f32_16x16x32_bf16 v[112:115], v[156:159], v[172:175], v[112:115]
	v_mfma_f32_16x16x32_bf16 v[80:83], v[148:151], v[194:197], v[80:83]
	v_mfma_f32_16x16x32_bf16 v[76:79], v[156:159], v[194:197], v[76:79]
	v_mfma_f32_16x16x32_bf16 v[72:75], v[148:151], v[202:205], v[72:75]
	v_mfma_f32_16x16x32_bf16 v[68:71], v[156:159], v[202:205], v[68:71]
	v_mfma_f32_16x16x32_bf16 v[124:127], v[152:155], v[168:171], v[124:127]
	v_mfma_f32_16x16x32_bf16 v[120:123], v[160:163], v[168:171], v[120:123]
	v_mfma_f32_16x16x32_bf16 v[116:119], v[152:155], v[176:179], v[116:119]
	v_mfma_f32_16x16x32_bf16 v[112:115], v[160:163], v[176:179], v[112:115]
	v_mfma_f32_16x16x32_bf16 v[80:83], v[152:155], v[198:201], v[80:83]
	v_mfma_f32_16x16x32_bf16 v[76:79], v[160:163], v[198:201], v[76:79]
	v_mfma_f32_16x16x32_bf16 v[72:75], v[152:155], v[206:209], v[72:75]
	v_mfma_f32_16x16x32_bf16 v[68:71], v[160:163], v[206:209], v[68:71]
	s_barrier
	s_add_i32 s44, s44, s50
	v_lshl_add_u64 v[210:211], s[36:37], 0, v[180:181]
	s_mov_b32 m0, s44
	ds_read_b128 v[164:167], v221 offset:16384
	ds_read_b128 v[168:171], v221 offset:17408
	ds_read_b128 v[172:175], v221 offset:18432
	ds_read_b128 v[176:179], v221 offset:19456
	ds_read_b128 v[194:197], v221 offset:20480
	ds_read_b128 v[198:201], v221 offset:21504
	ds_read_b128 v[202:205], v221 offset:22528
	ds_read_b128 v[206:209], v221 offset:23552
	global_load_lds_dwordx4 v[210:211], off
	s_add_i32 m0, s44, 0x2000
	s_add_u32 s44, s36, 0x40000
	v_lshl_add_u64 v[212:213], s[36:37], 0, v[188:189]
	s_addc_u32 s45, s37, 0
	s_add_i32 s31, s31, s50
	global_load_lds_dwordx4 v[212:213], off
	v_lshl_add_u64 v[214:215], s[44:45], 0, v[180:181]
	s_mov_b32 m0, s31
	v_lshl_add_u64 v[216:217], s[38:39], 0, v[188:189]
	global_load_lds_dwordx4 v[214:215], off
	v_lshl_add_u64 v[214:215], s[44:45], 0, v[188:189]
	s_add_i32 m0, s31, 0x2000
	s_nop 0
	global_load_lds_dwordx4 v[214:215], off
	v_lshl_add_u64 v[214:215], s[38:39], 0, v[180:181]
	s_mov_b32 m0, s51
	s_nop 0
	global_load_lds_dwordx4 v[214:215], off
	s_mov_b32 m0, s56
	s_nop 0
	global_load_lds_dwordx4 v[216:217], off
	s_waitcnt vmcnt(8)
	s_waitcnt lgkmcnt(0)
	s_barrier
	s_waitcnt lgkmcnt(0)
	v_mfma_f32_16x16x32_bf16 v[64:67], v[100:103], v[164:167], v[64:67]
	v_mfma_f32_16x16x32_bf16 v[60:63], v[108:111], v[164:167], v[60:63]
	v_mfma_f32_16x16x32_bf16 v[56:59], v[100:103], v[172:175], v[56:59]
	v_mfma_f32_16x16x32_bf16 v[52:55], v[108:111], v[172:175], v[52:55]
	v_mfma_f32_16x16x32_bf16 v[32:35], v[100:103], v[194:197], v[32:35]
	v_mfma_f32_16x16x32_bf16 v[28:31], v[108:111], v[194:197], v[28:31]
	v_mfma_f32_16x16x32_bf16 v[24:27], v[100:103], v[202:205], v[24:27]
	v_mfma_f32_16x16x32_bf16 v[12:15], v[108:111], v[202:205], v[12:15]
	v_mfma_f32_16x16x32_bf16 v[64:67], v[104:107], v[168:171], v[64:67]
	v_mfma_f32_16x16x32_bf16 v[60:63], v[128:131], v[168:171], v[60:63]
	v_mfma_f32_16x16x32_bf16 v[56:59], v[104:107], v[176:179], v[56:59]
	v_mfma_f32_16x16x32_bf16 v[52:55], v[128:131], v[176:179], v[52:55]
	v_mfma_f32_16x16x32_bf16 v[32:35], v[104:107], v[198:201], v[32:35]
	v_mfma_f32_16x16x32_bf16 v[28:31], v[128:131], v[198:201], v[28:31]
	v_mfma_f32_16x16x32_bf16 v[24:27], v[104:107], v[206:209], v[24:27]
	v_mfma_f32_16x16x32_bf16 v[12:15], v[128:131], v[206:209], v[12:15]
	v_mfma_f32_16x16x32_bf16 v[48:51], v[148:151], v[164:167], v[48:51]
	v_mfma_f32_16x16x32_bf16 v[44:47], v[156:159], v[164:167], v[44:47]
	v_mfma_f32_16x16x32_bf16 v[40:43], v[148:151], v[172:175], v[40:43]
	v_mfma_f32_16x16x32_bf16 v[36:39], v[156:159], v[172:175], v[36:39]
	v_mfma_f32_16x16x32_bf16 v[20:23], v[148:151], v[194:197], v[20:23]
	v_mfma_f32_16x16x32_bf16 v[16:19], v[156:159], v[194:197], v[16:19]
	v_mfma_f32_16x16x32_bf16 v[8:11], v[148:151], v[202:205], v[8:11]
	v_mfma_f32_16x16x32_bf16 v[4:7], v[156:159], v[202:205], v[4:7]
	v_mfma_f32_16x16x32_bf16 v[48:51], v[152:155], v[168:171], v[48:51]
	v_mfma_f32_16x16x32_bf16 v[44:47], v[160:163], v[168:171], v[44:47]
	v_mfma_f32_16x16x32_bf16 v[40:43], v[152:155], v[176:179], v[40:43]
	v_mfma_f32_16x16x32_bf16 v[36:39], v[160:163], v[176:179], v[36:39]
	v_mfma_f32_16x16x32_bf16 v[20:23], v[152:155], v[198:201], v[20:23]
	v_mfma_f32_16x16x32_bf16 v[16:19], v[160:163], v[198:201], v[16:19]
	v_mfma_f32_16x16x32_bf16 v[8:11], v[152:155], v[206:209], v[8:11]
	v_mfma_f32_16x16x32_bf16 v[4:7], v[160:163], v[206:209], v[4:7]
	s_barrier
	s_add_i32 s31, 0, 0x18000
	s_add_i32 s44, 0, 0x1c000
	v_add_u32_e32 v128, s31, v220
	v_add_u32_e32 v160, s44, v220
	ds_read_b128 v[100:103], v128
	ds_read_b128 v[104:107], v128 offset:1024
	ds_read_b128 v[108:111], v128 offset:2048
	ds_read_b128 v[128:131], v128 offset:3072
	ds_read_b128 v[148:151], v160
	ds_read_b128 v[152:155], v160 offset:1024
	ds_read_b128 v[156:159], v160 offset:2048
	ds_read_b128 v[160:163], v160 offset:3072
	s_add_u32 s38, s38, 0x40000
	s_addc_u32 s39, s39, 0
	s_mov_b32 m0, s57
	v_lshl_add_u64 v[218:219], s[38:39], 0, v[180:181]
	ds_read_b128 v[164:167], v221 offset:32768
	ds_read_b128 v[168:171], v221 offset:33792
	ds_read_b128 v[172:175], v221 offset:34816
	ds_read_b128 v[176:179], v221 offset:35840
	ds_read_b128 v[194:197], v221 offset:36864
	ds_read_b128 v[198:201], v221 offset:37888
	ds_read_b128 v[202:205], v221 offset:38912
	ds_read_b128 v[206:209], v221 offset:39936
	global_load_lds_dwordx4 v[218:219], off
	v_lshl_add_u64 v[218:219], s[38:39], 0, v[188:189]
	s_mov_b32 m0, s58
	s_nop 0
	global_load_lds_dwordx4 v[218:219], off
	s_waitcnt vmcnt(8)
	s_waitcnt lgkmcnt(0)
	s_barrier
	s_waitcnt lgkmcnt(0)
	v_mfma_f32_16x16x32_bf16 v[144:147], v[100:103], v[164:167], v[144:147]
	v_mfma_f32_16x16x32_bf16 v[140:143], v[108:111], v[164:167], v[140:143]
	v_mfma_f32_16x16x32_bf16 v[136:139], v[100:103], v[172:175], v[136:139]
	v_mfma_f32_16x16x32_bf16 v[132:135], v[108:111], v[172:175], v[132:135]
	v_mfma_f32_16x16x32_bf16 v[96:99], v[100:103], v[194:197], v[96:99]
	v_mfma_f32_16x16x32_bf16 v[92:95], v[108:111], v[194:197], v[92:95]
	v_mfma_f32_16x16x32_bf16 v[88:91], v[100:103], v[202:205], v[88:91]
	v_mfma_f32_16x16x32_bf16 v[84:87], v[108:111], v[202:205], v[84:87]
	v_mfma_f32_16x16x32_bf16 v[144:147], v[104:107], v[168:171], v[144:147]
	v_mfma_f32_16x16x32_bf16 v[140:143], v[128:131], v[168:171], v[140:143]
	v_mfma_f32_16x16x32_bf16 v[136:139], v[104:107], v[176:179], v[136:139]
	v_mfma_f32_16x16x32_bf16 v[132:135], v[128:131], v[176:179], v[132:135]
	v_mfma_f32_16x16x32_bf16 v[96:99], v[104:107], v[198:201], v[96:99]
	v_mfma_f32_16x16x32_bf16 v[92:95], v[128:131], v[198:201], v[92:95]
	v_mfma_f32_16x16x32_bf16 v[88:91], v[104:107], v[206:209], v[88:91]
	v_mfma_f32_16x16x32_bf16 v[84:87], v[128:131], v[206:209], v[84:87]
	v_mfma_f32_16x16x32_bf16 v[124:127], v[148:151], v[164:167], v[124:127]
	v_mfma_f32_16x16x32_bf16 v[120:123], v[156:159], v[164:167], v[120:123]
	v_mfma_f32_16x16x32_bf16 v[116:119], v[148:151], v[172:175], v[116:119]
	v_mfma_f32_16x16x32_bf16 v[112:115], v[156:159], v[172:175], v[112:115]
	v_mfma_f32_16x16x32_bf16 v[80:83], v[148:151], v[194:197], v[80:83]
	v_mfma_f32_16x16x32_bf16 v[76:79], v[156:159], v[194:197], v[76:79]
	v_mfma_f32_16x16x32_bf16 v[72:75], v[148:151], v[202:205], v[72:75]
	v_mfma_f32_16x16x32_bf16 v[68:71], v[156:159], v[202:205], v[68:71]
	v_mfma_f32_16x16x32_bf16 v[124:127], v[152:155], v[168:171], v[124:127]
	v_mfma_f32_16x16x32_bf16 v[120:123], v[160:163], v[168:171], v[120:123]
	v_mfma_f32_16x16x32_bf16 v[116:119], v[152:155], v[176:179], v[116:119]
	v_mfma_f32_16x16x32_bf16 v[112:115], v[160:163], v[176:179], v[112:115]
	v_mfma_f32_16x16x32_bf16 v[80:83], v[152:155], v[198:201], v[80:83]
	v_mfma_f32_16x16x32_bf16 v[76:79], v[160:163], v[198:201], v[76:79]
	v_mfma_f32_16x16x32_bf16 v[72:75], v[152:155], v[206:209], v[72:75]
	v_mfma_f32_16x16x32_bf16 v[68:71], v[160:163], v[206:209], v[68:71]
	s_barrier
	s_add_i32 s31, s31, s50
	v_lshl_add_u64 v[210:211], v[210:211], 0, s[52:53]
	s_mov_b32 m0, s31
	ds_read_b128 v[164:167], v221 offset:49152
	ds_read_b128 v[168:171], v221 offset:50176
	ds_read_b128 v[172:175], v221 offset:51200
	ds_read_b128 v[176:179], v221 offset:52224
	ds_read_b128 v[194:197], v221 offset:53248
	ds_read_b128 v[198:201], v221 offset:54272
	ds_read_b128 v[202:205], v221 offset:55296
	ds_read_b128 v[206:209], v221 offset:56320
	global_load_lds_dwordx4 v[210:211], off
	s_add_i32 m0, s31, 0x2000
	s_add_u32 s36, s36, 0x40080
	v_lshl_add_u64 v[210:211], v[212:213], 0, s[52:53]
	s_addc_u32 s37, s37, 0
	s_add_i32 s31, s44, s50
	global_load_lds_dwordx4 v[210:211], off
	v_lshl_add_u64 v[210:211], s[36:37], 0, v[180:181]
	s_mov_b32 m0, s31
	s_nop 0
	global_load_lds_dwordx4 v[210:211], off
	v_lshl_add_u64 v[210:211], s[36:37], 0, v[188:189]
	s_add_i32 m0, s31, 0x2000
	s_nop 0
	global_load_lds_dwordx4 v[210:211], off
	v_lshl_add_u64 v[210:211], v[214:215], 0, s[52:53]
	s_mov_b32 m0, s85
	s_nop 0
	global_load_lds_dwordx4 v[210:211], off
	v_lshl_add_u64 v[210:211], v[216:217], 0, s[52:53]
	s_mov_b32 m0, s86
	s_nop 0
	global_load_lds_dwordx4 v[210:211], off
	s_waitcnt vmcnt(8)
	s_waitcnt lgkmcnt(0)
	s_barrier
	s_waitcnt lgkmcnt(0)
	v_mfma_f32_16x16x32_bf16 v[64:67], v[100:103], v[164:167], v[64:67]
	v_mfma_f32_16x16x32_bf16 v[60:63], v[108:111], v[164:167], v[60:63]
	v_mfma_f32_16x16x32_bf16 v[56:59], v[100:103], v[172:175], v[56:59]
	v_mfma_f32_16x16x32_bf16 v[52:55], v[108:111], v[172:175], v[52:55]
	v_mfma_f32_16x16x32_bf16 v[32:35], v[100:103], v[194:197], v[32:35]
	v_mfma_f32_16x16x32_bf16 v[28:31], v[108:111], v[194:197], v[28:31]
	v_mfma_f32_16x16x32_bf16 v[24:27], v[100:103], v[202:205], v[24:27]
	v_mfma_f32_16x16x32_bf16 v[12:15], v[108:111], v[202:205], v[12:15]
	v_mfma_f32_16x16x32_bf16 v[64:67], v[104:107], v[168:171], v[64:67]
	v_mfma_f32_16x16x32_bf16 v[60:63], v[128:131], v[168:171], v[60:63]
	v_mfma_f32_16x16x32_bf16 v[56:59], v[104:107], v[176:179], v[56:59]
	v_mfma_f32_16x16x32_bf16 v[52:55], v[128:131], v[176:179], v[52:55]
	v_mfma_f32_16x16x32_bf16 v[32:35], v[104:107], v[198:201], v[32:35]
	v_mfma_f32_16x16x32_bf16 v[28:31], v[128:131], v[198:201], v[28:31]
	v_mfma_f32_16x16x32_bf16 v[24:27], v[104:107], v[206:209], v[24:27]
	v_mfma_f32_16x16x32_bf16 v[12:15], v[128:131], v[206:209], v[12:15]
	v_mfma_f32_16x16x32_bf16 v[48:51], v[148:151], v[164:167], v[48:51]
	v_mfma_f32_16x16x32_bf16 v[44:47], v[156:159], v[164:167], v[44:47]
	v_mfma_f32_16x16x32_bf16 v[40:43], v[148:151], v[172:175], v[40:43]
	v_mfma_f32_16x16x32_bf16 v[36:39], v[156:159], v[172:175], v[36:39]
	v_mfma_f32_16x16x32_bf16 v[20:23], v[148:151], v[194:197], v[20:23]
	v_mfma_f32_16x16x32_bf16 v[16:19], v[156:159], v[194:197], v[16:19]
	v_mfma_f32_16x16x32_bf16 v[8:11], v[148:151], v[202:205], v[8:11]
	v_mfma_f32_16x16x32_bf16 v[4:7], v[156:159], v[202:205], v[4:7]
	v_mfma_f32_16x16x32_bf16 v[48:51], v[152:155], v[168:171], v[48:51]
	v_mfma_f32_16x16x32_bf16 v[44:47], v[160:163], v[168:171], v[44:47]
	v_mfma_f32_16x16x32_bf16 v[40:43], v[152:155], v[176:179], v[40:43]
	v_mfma_f32_16x16x32_bf16 v[36:39], v[160:163], v[176:179], v[36:39]
	v_mfma_f32_16x16x32_bf16 v[20:23], v[152:155], v[198:201], v[20:23]
	v_mfma_f32_16x16x32_bf16 v[16:19], v[160:163], v[198:201], v[16:19]
	v_mfma_f32_16x16x32_bf16 v[8:11], v[152:155], v[206:209], v[8:11]
	v_mfma_f32_16x16x32_bf16 v[4:7], v[160:163], v[206:209], v[4:7]
	s_barrier
	s_add_u32 s34, s34, 0x100
	s_addc_u32 s35, s35, 0
	s_add_u32 s21, s21, 0x100
	s_addc_u32 s29, s29, 0
	s_cmp_ge_i32 s33, s1
	s_mov_b32 s31, s33
	s_cbranch_scc0 .LBB0_300
	s_and_b64 vcc, exec, s[14:15]
	s_cbranch_vccz .LBB0_303
	s_barrier

.LBB0_671:
	s_add_u32 s27, s30, 0xfffc0080
	s_addc_u32 s29, s31, -1
	s_add_i32 s33, 0, 0x10000
	s_cmp_eq_u32 s21, 12
	s_cselect_b32 s37, s0, s29
	s_cselect_b32 s36, s1, s27
	v_add_u32_e32 v144, s33, v157
	s_cselect_b32 s35, s2, s19
	s_cselect_b32 s34, s4, s5
	s_add_i32 s27, 0, 0x14000
	ds_read_b128 v[148:151], v144
	ds_read_b128 v[152:155], v144 offset:1024
	ds_read_b128 v[160:163], v144 offset:2048
	ds_read_b128 v[164:167], v144 offset:3072
	v_add_u32_e32 v144, s27, v157
	ds_read_b128 v[168:171], v144
	ds_read_b128 v[172:175], v144 offset:1024
	ds_read_b128 v[176:179], v144 offset:2048
	ds_read_b128 v[188:191], v144 offset:3072
	v_lshl_add_u64 v[144:145], s[30:31], 0, v[140:141]
	s_add_i32 m0, s43, 0xc000
	ds_read_b128 v[192:195], v158
	ds_read_b128 v[196:199], v158 offset:1024
	ds_read_b128 v[200:203], v158 offset:2048
	ds_read_b128 v[204:207], v158 offset:3072
	ds_read_b128 v[208:211], v158 offset:4096
	ds_read_b128 v[212:215], v158 offset:5120
	ds_read_b128 v[216:219], v158 offset:6144
	ds_read_b128 v[220:223], v158 offset:7168
	global_load_lds_dwordx4 v[144:145], off
	v_lshl_add_u64 v[144:145], s[30:31], 0, v[142:143]
	s_add_i32 m0, s43, 0xe000
	s_nop 0
	global_load_lds_dwordx4 v[144:145], off
	s_waitcnt vmcnt(8)
	s_waitcnt lgkmcnt(0)
	s_barrier
	s_waitcnt lgkmcnt(0)
	v_mfma_f32_16x16x32_bf16 v[128:131], v[148:151], v[192:195], v[128:131]
	v_mfma_f32_16x16x32_bf16 v[124:127], v[160:163], v[192:195], v[124:127]
	v_mfma_f32_16x16x32_bf16 v[112:115], v[148:151], v[200:203], v[112:115]
	v_mfma_f32_16x16x32_bf16 v[108:111], v[160:163], v[200:203], v[108:111]
	v_mfma_f32_16x16x32_bf16 v[96:99], v[148:151], v[208:211], v[96:99]
	v_mfma_f32_16x16x32_bf16 v[92:95], v[160:163], v[208:211], v[92:95]
	v_mfma_f32_16x16x32_bf16 v[80:83], v[148:151], v[216:219], v[80:83]
	v_mfma_f32_16x16x32_bf16 v[76:79], v[160:163], v[216:219], v[76:79]
	v_mfma_f32_16x16x32_bf16 v[128:131], v[152:155], v[196:199], v[128:131]
	v_mfma_f32_16x16x32_bf16 v[124:127], v[164:167], v[196:199], v[124:127]
	v_mfma_f32_16x16x32_bf16 v[112:115], v[152:155], v[204:207], v[112:115]
	v_mfma_f32_16x16x32_bf16 v[108:111], v[164:167], v[204:207], v[108:111]
	v_mfma_f32_16x16x32_bf16 v[96:99], v[152:155], v[212:215], v[96:99]
	v_mfma_f32_16x16x32_bf16 v[92:95], v[164:167], v[212:215], v[92:95]
	v_mfma_f32_16x16x32_bf16 v[80:83], v[152:155], v[220:223], v[80:83]
	v_mfma_f32_16x16x32_bf16 v[76:79], v[164:167], v[220:223], v[76:79]
	v_mfma_f32_16x16x32_bf16 v[120:123], v[168:171], v[192:195], v[120:123]
	v_mfma_f32_16x16x32_bf16 v[116:119], v[176:179], v[192:195], v[116:119]
	v_mfma_f32_16x16x32_bf16 v[104:107], v[168:171], v[200:203], v[104:107]
	v_mfma_f32_16x16x32_bf16 v[100:103], v[176:179], v[200:203], v[100:103]
	v_mfma_f32_16x16x32_bf16 v[88:91], v[168:171], v[208:211], v[88:91]
	v_mfma_f32_16x16x32_bf16 v[84:87], v[176:179], v[208:211], v[84:87]
	v_mfma_f32_16x16x32_bf16 v[72:75], v[168:171], v[216:219], v[72:75]
	v_mfma_f32_16x16x32_bf16 v[68:71], v[176:179], v[216:219], v[68:71]
	v_mfma_f32_16x16x32_bf16 v[120:123], v[172:175], v[196:199], v[120:123]
	v_mfma_f32_16x16x32_bf16 v[116:119], v[188:191], v[196:199], v[116:119]
	v_mfma_f32_16x16x32_bf16 v[104:107], v[172:175], v[204:207], v[104:107]
	v_mfma_f32_16x16x32_bf16 v[100:103], v[188:191], v[204:207], v[100:103]
	v_mfma_f32_16x16x32_bf16 v[88:91], v[172:175], v[212:215], v[88:91]
	v_mfma_f32_16x16x32_bf16 v[84:87], v[188:191], v[212:215], v[84:87]
	v_mfma_f32_16x16x32_bf16 v[72:75], v[172:175], v[220:223], v[72:75]
	v_mfma_f32_16x16x32_bf16 v[68:71], v[188:191], v[220:223], v[68:71]
	s_barrier
	s_add_i32 s29, s33, s42
	v_lshl_add_u64 v[144:145], s[34:35], 0, v[134:135]
	s_mov_b32 m0, s29
	ds_read_b128 v[192:195], v158 offset:16384
	ds_read_b128 v[196:199], v158 offset:17408
	ds_read_b128 v[200:203], v158 offset:18432
	ds_read_b128 v[204:207], v158 offset:19456
	ds_read_b128 v[208:211], v158 offset:20480
	ds_read_b128 v[212:215], v158 offset:21504
	ds_read_b128 v[216:219], v158 offset:22528
	ds_read_b128 v[220:223], v158 offset:23552
	global_load_lds_dwordx4 v[144:145], off
	s_add_i32 m0, s29, 0x2000
	s_add_u32 s44, s34, 0x40000
	v_lshl_add_u64 v[224:225], s[34:35], 0, v[138:139]
	s_addc_u32 s45, s35, 0
	s_add_i32 s27, s27, s42
	global_load_lds_dwordx4 v[224:225], off
	v_lshl_add_u64 v[226:227], s[44:45], 0, v[134:135]
	s_mov_b32 m0, s27
	v_lshl_add_u64 v[228:229], s[36:37], 0, v[136:137]
	global_load_lds_dwordx4 v[226:227], off
	v_lshl_add_u64 v[226:227], s[44:45], 0, v[138:139]
	s_add_i32 m0, s27, 0x2000
	s_nop 0
	global_load_lds_dwordx4 v[226:227], off
	v_lshl_add_u64 v[226:227], s[36:37], 0, v[132:133]
	s_mov_b32 m0, s43
	s_nop 0
	global_load_lds_dwordx4 v[226:227], off
	s_mov_b32 m0, s48
	s_nop 0
	global_load_lds_dwordx4 v[228:229], off
	s_waitcnt vmcnt(8)
	s_waitcnt lgkmcnt(0)
	s_barrier
	s_waitcnt lgkmcnt(0)
	v_mfma_f32_16x16x32_bf16 v[64:67], v[148:151], v[192:195], v[64:67]
	v_mfma_f32_16x16x32_bf16 v[60:63], v[160:163], v[192:195], v[60:63]
	v_mfma_f32_16x16x32_bf16 v[48:51], v[148:151], v[200:203], v[48:51]
	v_mfma_f32_16x16x32_bf16 v[44:47], v[160:163], v[200:203], v[44:47]
	v_mfma_f32_16x16x32_bf16 v[32:35], v[148:151], v[208:211], v[32:35]
	v_mfma_f32_16x16x32_bf16 v[28:31], v[160:163], v[208:211], v[28:31]
	v_mfma_f32_16x16x32_bf16 v[16:19], v[148:151], v[216:219], v[16:19]
	v_mfma_f32_16x16x32_bf16 v[12:15], v[160:163], v[216:219], v[12:15]
	v_mfma_f32_16x16x32_bf16 v[64:67], v[152:155], v[196:199], v[64:67]
	v_mfma_f32_16x16x32_bf16 v[60:63], v[164:167], v[196:199], v[60:63]
	v_mfma_f32_16x16x32_bf16 v[48:51], v[152:155], v[204:207], v[48:51]
	v_mfma_f32_16x16x32_bf16 v[44:47], v[164:167], v[204:207], v[44:47]
	v_mfma_f32_16x16x32_bf16 v[32:35], v[152:155], v[212:215], v[32:35]
	v_mfma_f32_16x16x32_bf16 v[28:31], v[164:167], v[212:215], v[28:31]
	v_mfma_f32_16x16x32_bf16 v[16:19], v[152:155], v[220:223], v[16:19]
	v_mfma_f32_16x16x32_bf16 v[12:15], v[164:167], v[220:223], v[12:15]
	v_mfma_f32_16x16x32_bf16 v[56:59], v[168:171], v[192:195], v[56:59]
	v_mfma_f32_16x16x32_bf16 v[52:55], v[176:179], v[192:195], v[52:55]
	v_mfma_f32_16x16x32_bf16 v[40:43], v[168:171], v[200:203], v[40:43]
	v_mfma_f32_16x16x32_bf16 v[36:39], v[176:179], v[200:203], v[36:39]
	v_mfma_f32_16x16x32_bf16 v[24:27], v[168:171], v[208:211], v[24:27]
	v_mfma_f32_16x16x32_bf16 v[20:23], v[176:179], v[208:211], v[20:23]
	v_mfma_f32_16x16x32_bf16 v[8:11], v[168:171], v[216:219], v[8:11]
	v_mfma_f32_16x16x32_bf16 v[4:7], v[176:179], v[216:219], v[4:7]
	v_mfma_f32_16x16x32_bf16 v[56:59], v[172:175], v[196:199], v[56:59]
	v_mfma_f32_16x16x32_bf16 v[52:55], v[188:191], v[196:199], v[52:55]
	v_mfma_f32_16x16x32_bf16 v[40:43], v[172:175], v[204:207], v[40:43]
	v_mfma_f32_16x16x32_bf16 v[36:39], v[188:191], v[204:207], v[36:39]
	v_mfma_f32_16x16x32_bf16 v[24:27], v[172:175], v[212:215], v[24:27]
	v_mfma_f32_16x16x32_bf16 v[20:23], v[188:191], v[212:215], v[20:23]
	v_mfma_f32_16x16x32_bf16 v[8:11], v[172:175], v[220:223], v[8:11]
	v_mfma_f32_16x16x32_bf16 v[4:7], v[188:191], v[220:223], v[4:7]
	s_barrier
	s_add_i32 s27, 0, 0x18000
	v_add_u32_e32 v146, s27, v157
	s_add_i32 s29, 0, 0x1c000
	ds_read_b128 v[148:151], v146
	ds_read_b128 v[152:155], v146 offset:1024
	ds_read_b128 v[160:163], v146 offset:2048
	ds_read_b128 v[164:167], v146 offset:3072
	v_add_u32_e32 v146, s29, v157
	ds_read_b128 v[168:171], v146
	ds_read_b128 v[172:175], v146 offset:1024
	ds_read_b128 v[176:179], v146 offset:2048
	ds_read_b128 v[188:191], v146 offset:3072
	s_add_u32 s36, s36, 0x40000
	s_addc_u32 s37, s37, 0
	s_mov_b32 m0, s50
	v_lshl_add_u64 v[230:231], s[36:37], 0, v[132:133]
	ds_read_b128 v[192:195], v158 offset:32768
	ds_read_b128 v[196:199], v158 offset:33792
	ds_read_b128 v[200:203], v158 offset:34816
	ds_read_b128 v[204:207], v158 offset:35840
	ds_read_b128 v[208:211], v158 offset:36864
	ds_read_b128 v[212:215], v158 offset:37888
	ds_read_b128 v[216:219], v158 offset:38912
	ds_read_b128 v[220:223], v158 offset:39936
	global_load_lds_dwordx4 v[230:231], off
	v_lshl_add_u64 v[230:231], s[36:37], 0, v[136:137]
	s_mov_b32 m0, s51
	s_nop 0
	global_load_lds_dwordx4 v[230:231], off
	s_waitcnt vmcnt(8)
	s_waitcnt lgkmcnt(0)
	s_barrier
	s_waitcnt lgkmcnt(0)
	v_mfma_f32_16x16x32_bf16 v[128:131], v[148:151], v[192:195], v[128:131]
	v_mfma_f32_16x16x32_bf16 v[124:127], v[160:163], v[192:195], v[124:127]
	v_mfma_f32_16x16x32_bf16 v[112:115], v[148:151], v[200:203], v[112:115]
	v_mfma_f32_16x16x32_bf16 v[108:111], v[160:163], v[200:203], v[108:111]
	v_mfma_f32_16x16x32_bf16 v[96:99], v[148:151], v[208:211], v[96:99]
	v_mfma_f32_16x16x32_bf16 v[92:95], v[160:163], v[208:211], v[92:95]
	v_mfma_f32_16x16x32_bf16 v[80:83], v[148:151], v[216:219], v[80:83]
	v_mfma_f32_16x16x32_bf16 v[76:79], v[160:163], v[216:219], v[76:79]
	v_mfma_f32_16x16x32_bf16 v[128:131], v[152:155], v[196:199], v[128:131]
	v_mfma_f32_16x16x32_bf16 v[124:127], v[164:167], v[196:199], v[124:127]
	v_mfma_f32_16x16x32_bf16 v[112:115], v[152:155], v[204:207], v[112:115]
	v_mfma_f32_16x16x32_bf16 v[108:111], v[164:167], v[204:207], v[108:111]
	v_mfma_f32_16x16x32_bf16 v[96:99], v[152:155], v[212:215], v[96:99]
	v_mfma_f32_16x16x32_bf16 v[92:95], v[164:167], v[212:215], v[92:95]
	v_mfma_f32_16x16x32_bf16 v[80:83], v[152:155], v[220:223], v[80:83]
	v_mfma_f32_16x16x32_bf16 v[76:79], v[164:167], v[220:223], v[76:79]
	v_mfma_f32_16x16x32_bf16 v[120:123], v[168:171], v[192:195], v[120:123]
	v_mfma_f32_16x16x32_bf16 v[116:119], v[176:179], v[192:195], v[116:119]
	v_mfma_f32_16x16x32_bf16 v[104:107], v[168:171], v[200:203], v[104:107]
	v_mfma_f32_16x16x32_bf16 v[100:103], v[176:179], v[200:203], v[100:103]
	v_mfma_f32_16x16x32_bf16 v[88:91], v[168:171], v[208:211], v[88:91]
	v_mfma_f32_16x16x32_bf16 v[84:87], v[176:179], v[208:211], v[84:87]
	v_mfma_f32_16x16x32_bf16 v[72:75], v[168:171], v[216:219], v[72:75]
	v_mfma_f32_16x16x32_bf16 v[68:71], v[176:179], v[216:219], v[68:71]
	v_mfma_f32_16x16x32_bf16 v[120:123], v[172:175], v[196:199], v[120:123]
	v_mfma_f32_16x16x32_bf16 v[116:119], v[188:191], v[196:199], v[116:119]
	v_mfma_f32_16x16x32_bf16 v[104:107], v[172:175], v[204:207], v[104:107]
	v_mfma_f32_16x16x32_bf16 v[100:103], v[188:191], v[204:207], v[100:103]
	v_mfma_f32_16x16x32_bf16 v[88:91], v[172:175], v[212:215], v[88:91]
	v_mfma_f32_16x16x32_bf16 v[84:87], v[188:191], v[212:215], v[84:87]
	v_mfma_f32_16x16x32_bf16 v[72:75], v[172:175], v[220:223], v[72:75]
	v_mfma_f32_16x16x32_bf16 v[68:71], v[188:191], v[220:223], v[68:71]
	s_barrier
	s_add_i32 s27, s27, s42
	v_lshl_add_u64 v[144:145], v[144:145], 0, s[52:53]
	s_mov_b32 m0, s27
	ds_read_b128 v[192:195], v158 offset:49152
	ds_read_b128 v[196:199], v158 offset:50176
	ds_read_b128 v[200:203], v158 offset:51200
	ds_read_b128 v[204:207], v158 offset:52224
	ds_read_b128 v[208:211], v158 offset:53248
	ds_read_b128 v[212:215], v158 offset:54272
	ds_read_b128 v[216:219], v158 offset:55296
	ds_read_b128 v[220:223], v158 offset:56320
	global_load_lds_dwordx4 v[144:145], off
	s_add_i32 m0, s27, 0x2000
	s_add_u32 s34, s34, 0x40080
	v_lshl_add_u64 v[144:145], v[224:225], 0, s[52:53]
	s_addc_u32 s35, s35, 0
	s_add_i32 s27, s29, s42
	global_load_lds_dwordx4 v[144:145], off
	v_lshl_add_u64 v[144:145], s[34:35], 0, v[134:135]
	s_mov_b32 m0, s27
	s_nop 0
	global_load_lds_dwordx4 v[144:145], off
	v_lshl_add_u64 v[144:145], s[34:35], 0, v[138:139]
	s_add_i32 m0, s27, 0x2000
	s_nop 0
	global_load_lds_dwordx4 v[144:145], off
	v_lshl_add_u64 v[144:145], v[226:227], 0, s[52:53]
	s_mov_b32 m0, s58
	s_nop 0
	global_load_lds_dwordx4 v[144:145], off
	v_lshl_add_u64 v[144:145], v[228:229], 0, s[52:53]
	s_mov_b32 m0, s59
	s_nop 0
	global_load_lds_dwordx4 v[144:145], off
	s_waitcnt vmcnt(8)
	s_waitcnt lgkmcnt(0)
	s_barrier
	s_waitcnt lgkmcnt(0)
	v_mfma_f32_16x16x32_bf16 v[64:67], v[148:151], v[192:195], v[64:67]
	v_mfma_f32_16x16x32_bf16 v[60:63], v[160:163], v[192:195], v[60:63]
	v_mfma_f32_16x16x32_bf16 v[48:51], v[148:151], v[200:203], v[48:51]
	v_mfma_f32_16x16x32_bf16 v[44:47], v[160:163], v[200:203], v[44:47]
	v_mfma_f32_16x16x32_bf16 v[32:35], v[148:151], v[208:211], v[32:35]
	v_mfma_f32_16x16x32_bf16 v[28:31], v[160:163], v[208:211], v[28:31]
	v_mfma_f32_16x16x32_bf16 v[16:19], v[148:151], v[216:219], v[16:19]
	v_mfma_f32_16x16x32_bf16 v[12:15], v[160:163], v[216:219], v[12:15]
	v_mfma_f32_16x16x32_bf16 v[64:67], v[152:155], v[196:199], v[64:67]
	v_mfma_f32_16x16x32_bf16 v[60:63], v[164:167], v[196:199], v[60:63]
	v_mfma_f32_16x16x32_bf16 v[48:51], v[152:155], v[204:207], v[48:51]
	v_mfma_f32_16x16x32_bf16 v[44:47], v[164:167], v[204:207], v[44:47]
	v_mfma_f32_16x16x32_bf16 v[32:35], v[152:155], v[212:215], v[32:35]
	v_mfma_f32_16x16x32_bf16 v[28:31], v[164:167], v[212:215], v[28:31]
	v_mfma_f32_16x16x32_bf16 v[16:19], v[152:155], v[220:223], v[16:19]
	v_mfma_f32_16x16x32_bf16 v[12:15], v[164:167], v[220:223], v[12:15]
	v_mfma_f32_16x16x32_bf16 v[56:59], v[168:171], v[192:195], v[56:59]
	v_mfma_f32_16x16x32_bf16 v[52:55], v[176:179], v[192:195], v[52:55]
	v_mfma_f32_16x16x32_bf16 v[40:43], v[168:171], v[200:203], v[40:43]
	v_mfma_f32_16x16x32_bf16 v[36:39], v[176:179], v[200:203], v[36:39]
	v_mfma_f32_16x16x32_bf16 v[24:27], v[168:171], v[208:211], v[24:27]
	v_mfma_f32_16x16x32_bf16 v[20:23], v[176:179], v[208:211], v[20:23]
	v_mfma_f32_16x16x32_bf16 v[8:11], v[168:171], v[216:219], v[8:11]
	v_mfma_f32_16x16x32_bf16 v[4:7], v[176:179], v[216:219], v[4:7]
	v_mfma_f32_16x16x32_bf16 v[56:59], v[172:175], v[196:199], v[56:59]
	v_mfma_f32_16x16x32_bf16 v[52:55], v[188:191], v[196:199], v[52:55]
	v_mfma_f32_16x16x32_bf16 v[40:43], v[172:175], v[204:207], v[40:43]
	v_mfma_f32_16x16x32_bf16 v[36:39], v[188:191], v[204:207], v[36:39]
	v_mfma_f32_16x16x32_bf16 v[24:27], v[172:175], v[212:215], v[24:27]
	v_mfma_f32_16x16x32_bf16 v[20:23], v[188:191], v[212:215], v[20:23]
	v_mfma_f32_16x16x32_bf16 v[8:11], v[172:175], v[220:223], v[8:11]
	v_mfma_f32_16x16x32_bf16 v[4:7], v[188:191], v[220:223], v[4:7]
	s_barrier
	s_add_i32 s21, s21, 2
	s_add_u32 s30, s30, 0x100
	s_addc_u32 s31, s31, 0
	s_add_u32 s5, s5, 0x100
	s_addc_u32 s19, s19, 0
	s_cmp_gt_u32 s21, 13
	s_cbranch_scc0 .LBB0_671
	s_and_b64 vcc, exec, s[16:17]
	s_cbranch_vccz .LBB0_674
	s_barrier
